# GEMM K-loops: removed the redundant second lgkmcnt(0) after each phase barrier and the back-to-back setprio 0/1 pair in the middle of each MFMA run (24 + 24 instructions across six loops), on top of v
# baseline (speedup 1.0000x reference)
; #define PG8_STAGE(bufoff, gbase, voff) do { _Pragma("unroll") for (int _i = 0; _i < 2; ++_i) \
;         __builtin_amdgcn_global_load_lds((const unsigned*)((const char*)(gbase) + (voff)[_i]), (LAS unsigned*)(lds + (bufoff) + ldsw + _i * 8192), 16, 0, 0); } while (0)
; #define PG8_LDA(dst, b, h) do { _Pragma("unroll") for (int m = 0; m < 4; ++m) _Pragma("unroll") for (int k = 0; k < 2; ++k) dst[m][k] = *(const LAS bf16x8*)(lds + PG8_SA(b, h) + aoff + m * 2048 + k * 1024); } while (0)
; #define PG8_LDB(dst, b, h) do { _Pragma("unroll") for (int n = 0; n < 2; ++n) _Pragma("unroll") for (int k = 0; k < 2; ++k) dst[n][k] = *(const LAS bf16x8*)(lds + PG8_SB(b, h) + boff + n * 2048 + k * 1024); } while (0)
; #define PG8_MMA(ai, bj, At, Bt) do { __builtin_amdgcn_s_setprio(1); _Pragma("unroll") for (int m = 0; m < 4; ++m) _Pragma("unroll") for (int n = 0; n < 2; ++n) _Pragma("unroll") for (int k = 0; k < 2; ++k) \
;         acc[ai][bj][m][n] = __builtin_amdgcn_mfma_f32_16x16x32_bf16(Bt[n][k], At[m][k], acc[ai][bj][m][n], 0, 0, 0); __builtin_amdgcn_s_setprio(0); } while (0)
; #define PG8_WAIT_V(n) asm volatile("s_waitcnt vmcnt(" #n ")" ::: "memory")
; #define PG8_WAIT_L(n) asm volatile("s_waitcnt lgkmcnt(" #n ")" ::: "memory")
; #define PG8_BAR __builtin_amdgcn_s_barrier()
; #define PG8_SCHED __builtin_amdgcn_sched_barrier(0)
; template <class Epi>
; __device__ __forceinline__ void gemm_phase(LAS unsigned char* lds, const Gemm g, const StaticOrder& S, const Epi& E, const int wid) {
;     ...
;         for (int t = 0; t < nt; t += 2) {
;             const bool last = (t == nt - 2);
;             const char* a1 = cA + (size_t)(t + 1) * kstep;
;             const char* a2 = last ? nA : cA + (size_t)(t + 2) * kstep; const char* b2 = last ? nB : cB + (size_t)(t + 2) * kstep;
;             const char* a3 = a2 + kstep; const char* b3 = b2 + kstep;
;             PG8_LDB(B0, 0, 0); PG8_LDB(B1, 0, 1); PG8_SCHED; PG8_LDA(At, 0, 0); PG8_STAGE(PG8_SA(1, 1), a1 + hstepA, voffA);
;             PG8_WAIT_V(8); PG8_WAIT_L(0); PG8_BAR; PG8_MMA(0, 0, At, B0); PG8_MMA(0, 1, At, B1); PG8_BAR; PG8_SCHED;
;             PG8_LDA(At, 0, 1); PG8_STAGE(PG8_SB(0, 0), b2, voffB); PG8_STAGE(PG8_SB(0, 1), b2 + hstepB, voffB); PG8_STAGE(PG8_SA(0, 0), a2, voffA);
;             PG8_WAIT_V(8); PG8_WAIT_L(0); PG8_BAR; PG8_MMA(1, 0, At, B0); PG8_MMA(1, 1, At, B1); PG8_BAR; PG8_SCHED;
.LBB0_157:
	ds_read_b128 v[150:153], v157
	ds_read_b128 v[160:163], v157 offset:1024
	ds_read_b128 v[164:167], v157 offset:2048
	ds_read_b128 v[168:171], v157 offset:3072
	ds_read_b128 v[172:175], v158
	ds_read_b128 v[176:179], v158 offset:1024
	ds_read_b128 v[180:183], v158 offset:2048
	ds_read_b128 v[184:187], v158 offset:3072
	s_add_u32 s8, s10, 0x100
	s_addc_u32 s9, s11, 0
	s_cmp_eq_u32 s60, 28
	s_cselect_b32 s59, s51, s9
	s_cselect_b32 s58, s50, s8
	s_cselect_b32 s57, s20, s55
	s_cselect_b32 s56, s21, s49
	s_add_i32 m0, s0, 0xc000
	s_nop 0
	global_load_lds_dwordx4 v142, s[10:11]
	s_add_i32 m0, s0, 0xe000
	s_nop 0
	global_load_lds_dwordx4 v144, s[10:11]
	ds_read_b128 v[188:191], v159
	ds_read_b128 v[192:195], v159 offset:1024
	ds_read_b128 v[196:199], v159 offset:2048
	ds_read_b128 v[200:203], v159 offset:3072
	ds_read_b128 v[204:207], v159 offset:4096
	ds_read_b128 v[208:211], v159 offset:5120
	ds_read_b128 v[212:215], v159 offset:6144
	ds_read_b128 v[216:219], v159 offset:7168
	s_waitcnt vmcnt(8)
	s_waitcnt lgkmcnt(0)
	s_barrier
	s_setprio 1
	v_mfma_f32_16x16x32_bf16 v[124:127], v[150:153], v[188:191], v[124:127]
	v_mfma_f32_16x16x32_bf16 v[120:123], v[164:167], v[188:191], v[120:123]
	v_mfma_f32_16x16x32_bf16 v[116:119], v[150:153], v[196:199], v[116:119]
	v_mfma_f32_16x16x32_bf16 v[112:115], v[164:167], v[196:199], v[112:115]
	v_mfma_f32_16x16x32_bf16 v[108:111], v[150:153], v[204:207], v[108:111]
	v_mfma_f32_16x16x32_bf16 v[104:107], v[164:167], v[204:207], v[104:107]
	v_mfma_f32_16x16x32_bf16 v[100:103], v[150:153], v[212:215], v[100:103]
	v_mfma_f32_16x16x32_bf16 v[96:99], v[164:167], v[212:215], v[96:99]
	v_mfma_f32_16x16x32_bf16 v[124:127], v[160:163], v[192:195], v[124:127]
	v_mfma_f32_16x16x32_bf16 v[120:123], v[168:171], v[192:195], v[120:123]
	v_mfma_f32_16x16x32_bf16 v[116:119], v[160:163], v[200:203], v[116:119]
	v_mfma_f32_16x16x32_bf16 v[112:115], v[168:171], v[200:203], v[112:115]
	v_mfma_f32_16x16x32_bf16 v[108:111], v[160:163], v[208:211], v[108:111]
	v_mfma_f32_16x16x32_bf16 v[104:107], v[168:171], v[208:211], v[104:107]
	v_mfma_f32_16x16x32_bf16 v[100:103], v[160:163], v[216:219], v[100:103]
	v_mfma_f32_16x16x32_bf16 v[96:99], v[168:171], v[216:219], v[96:99]
	v_mfma_f32_16x16x32_bf16 v[60:63], v[172:175], v[188:191], v[60:63]
	v_mfma_f32_16x16x32_bf16 v[56:59], v[180:183], v[188:191], v[56:59]
	v_mfma_f32_16x16x32_bf16 v[52:55], v[172:175], v[196:199], v[52:55]
	v_mfma_f32_16x16x32_bf16 v[48:51], v[180:183], v[196:199], v[48:51]
	v_mfma_f32_16x16x32_bf16 v[44:47], v[172:175], v[204:207], v[44:47]
	v_mfma_f32_16x16x32_bf16 v[40:43], v[180:183], v[204:207], v[40:43]
	v_mfma_f32_16x16x32_bf16 v[36:39], v[172:175], v[212:215], v[36:39]
	v_mfma_f32_16x16x32_bf16 v[32:35], v[180:183], v[212:215], v[32:35]
	v_mfma_f32_16x16x32_bf16 v[60:63], v[176:179], v[192:195], v[60:63]
	v_mfma_f32_16x16x32_bf16 v[56:59], v[184:187], v[192:195], v[56:59]
	v_mfma_f32_16x16x32_bf16 v[52:55], v[176:179], v[200:203], v[52:55]
	v_mfma_f32_16x16x32_bf16 v[48:51], v[184:187], v[200:203], v[48:51]
	v_mfma_f32_16x16x32_bf16 v[44:47], v[176:179], v[208:211], v[44:47]
	v_mfma_f32_16x16x32_bf16 v[40:43], v[184:187], v[208:211], v[40:43]
	v_mfma_f32_16x16x32_bf16 v[36:39], v[176:179], v[216:219], v[36:39]
	v_mfma_f32_16x16x32_bf16 v[32:35], v[184:187], v[216:219], v[32:35]
	s_setprio 0
	s_barrier
	s_add_i32 s10, s68, s94
	s_mov_b32 m0, s10
	s_nop 0
	global_load_lds_dwordx4 v130, s[56:57]
	s_add_i32 m0, s10, 0x2000
	s_add_u32 s10, s56, 0x80000
	s_addc_u32 s11, s57, 0
	s_add_i32 s24, s69, s94
	global_load_lds_dwordx4 v134, s[56:57]
	s_mov_b32 m0, s24
	s_nop 0
	global_load_lds_dwordx4 v130, s[10:11]
	s_add_i32 m0, s24, 0x2000
	s_nop 0
	global_load_lds_dwordx4 v134, s[10:11]
	s_mov_b32 m0, s0
	s_nop 0
	global_load_lds_dwordx4 v128, s[58:59]
	s_mov_b32 m0, s1
	s_nop 0
	global_load_lds_dwordx4 v132, s[58:59]
	ds_read_b128 v[188:191], v159 offset:16384
	ds_read_b128 v[192:195], v159 offset:17408
	ds_read_b128 v[196:199], v159 offset:18432
	ds_read_b128 v[200:203], v159 offset:19456
	ds_read_b128 v[204:207], v159 offset:20480
	ds_read_b128 v[208:211], v159 offset:21504
	ds_read_b128 v[212:215], v159 offset:22528
	ds_read_b128 v[216:219], v159 offset:23552
	s_waitcnt vmcnt(8)
	s_waitcnt lgkmcnt(0)
	s_barrier
	s_setprio 1
	v_mfma_f32_16x16x32_bf16 v[92:95], v[150:153], v[188:191], v[92:95]
	v_mfma_f32_16x16x32_bf16 v[88:91], v[164:167], v[188:191], v[88:91]
	v_mfma_f32_16x16x32_bf16 v[84:87], v[150:153], v[196:199], v[84:87]
	v_mfma_f32_16x16x32_bf16 v[80:83], v[164:167], v[196:199], v[80:83]
	v_mfma_f32_16x16x32_bf16 v[76:79], v[150:153], v[204:207], v[76:79]
	v_mfma_f32_16x16x32_bf16 v[72:75], v[164:167], v[204:207], v[72:75]
	v_mfma_f32_16x16x32_bf16 v[68:71], v[150:153], v[212:215], v[68:71]
	v_mfma_f32_16x16x32_bf16 v[64:67], v[164:167], v[212:215], v[64:67]
	v_mfma_f32_16x16x32_bf16 v[92:95], v[160:163], v[192:195], v[92:95]
	v_mfma_f32_16x16x32_bf16 v[88:91], v[168:171], v[192:195], v[88:91]
	v_mfma_f32_16x16x32_bf16 v[84:87], v[160:163], v[200:203], v[84:87]
	v_mfma_f32_16x16x32_bf16 v[80:83], v[168:171], v[200:203], v[80:83]
	v_mfma_f32_16x16x32_bf16 v[76:79], v[160:163], v[208:211], v[76:79]
	v_mfma_f32_16x16x32_bf16 v[72:75], v[168:171], v[208:211], v[72:75]
	v_mfma_f32_16x16x32_bf16 v[68:71], v[160:163], v[216:219], v[68:71]
	v_mfma_f32_16x16x32_bf16 v[64:67], v[168:171], v[216:219], v[64:67]
	v_mfma_f32_16x16x32_bf16 v[28:31], v[172:175], v[188:191], v[28:31]
	v_mfma_f32_16x16x32_bf16 v[24:27], v[180:183], v[188:191], v[24:27]
	v_mfma_f32_16x16x32_bf16 v[20:23], v[172:175], v[196:199], v[20:23]
	v_mfma_f32_16x16x32_bf16 v[16:19], v[180:183], v[196:199], v[16:19]
	v_mfma_f32_16x16x32_bf16 v[12:15], v[172:175], v[204:207], v[12:15]
	v_mfma_f32_16x16x32_bf16 v[8:11], v[180:183], v[204:207], v[8:11]
	v_mfma_f32_16x16x32_bf16 v[4:7], v[172:175], v[212:215], v[4:7]
	v_mfma_f32_16x16x32_bf16 v[0:3], v[180:183], v[212:215], v[0:3]
	v_mfma_f32_16x16x32_bf16 v[28:31], v[176:179], v[192:195], v[28:31]
	v_mfma_f32_16x16x32_bf16 v[24:27], v[184:187], v[192:195], v[24:27]
	v_mfma_f32_16x16x32_bf16 v[20:23], v[176:179], v[200:203], v[20:23]
	v_mfma_f32_16x16x32_bf16 v[16:19], v[184:187], v[200:203], v[16:19]
	v_mfma_f32_16x16x32_bf16 v[12:15], v[176:179], v[208:211], v[12:15]
	v_mfma_f32_16x16x32_bf16 v[8:11], v[184:187], v[208:211], v[8:11]
	v_mfma_f32_16x16x32_bf16 v[4:7], v[176:179], v[216:219], v[4:7]
	v_mfma_f32_16x16x32_bf16 v[0:3], v[184:187], v[216:219], v[0:3]
	s_setprio 0
	s_barrier
; #define PG8_STAGE(bufoff, gbase, voff) do { _Pragma("unroll") for (int _i = 0; _i < 2; ++_i) \
;         __builtin_amdgcn_global_load_lds((const unsigned*)((const char*)(gbase) + (voff)[_i]), (LAS unsigned*)(lds + (bufoff) + ldsw + _i * 8192), 16, 0, 0); } while (0)
; #define PG8_LDA(dst, b, h) do { _Pragma("unroll") for (int m = 0; m < 4; ++m) _Pragma("unroll") for (int k = 0; k < 2; ++k) dst[m][k] = *(const LAS bf16x8*)(lds + PG8_SA(b, h) + aoff + m * 2048 + k * 1024); } while (0)
; #define PG8_LDB(dst, b, h) do { _Pragma("unroll") for (int n = 0; n < 2; ++n) _Pragma("unroll") for (int k = 0; k < 2; ++k) dst[n][k] = *(const LAS bf16x8*)(lds + PG8_SB(b, h) + boff + n * 2048 + k * 1024); } while (0)
; #define PG8_MMA(ai, bj, At, Bt) do { __builtin_amdgcn_s_setprio(1); _Pragma("unroll") for (int m = 0; m < 4; ++m) _Pragma("unroll") for (int n = 0; n < 2; ++n) _Pragma("unroll") for (int k = 0; k < 2; ++k) \
;         acc[ai][bj][m][n] = __builtin_amdgcn_mfma_f32_16x16x32_bf16(Bt[n][k], At[m][k], acc[ai][bj][m][n], 0, 0, 0); __builtin_amdgcn_s_setprio(0); } while (0)
; #define PG8_WAIT_V(n) asm volatile("s_waitcnt vmcnt(" #n ")" ::: "memory")
; #define PG8_WAIT_L(n) asm volatile("s_waitcnt lgkmcnt(" #n ")" ::: "memory")
; #define PG8_BAR __builtin_amdgcn_s_barrier()
; #define PG8_SCHED __builtin_amdgcn_sched_barrier(0)
; template <class Epi>
; __device__ __forceinline__ void gemm_phase(LAS unsigned char* lds, const Gemm g, const StaticOrder& S, const Epi& E, const int wid) {
;     ...
;             PG8_LDB(B0, 1, 0); PG8_LDB(B1, 1, 1); PG8_SCHED; PG8_LDA(At, 1, 0); PG8_STAGE(PG8_SA(0, 1), a2 + hstepA, voffA);
;             PG8_WAIT_V(8); PG8_WAIT_L(0); PG8_BAR; PG8_MMA(0, 0, At, B0); PG8_MMA(0, 1, At, B1); PG8_BAR; PG8_SCHED;
;             PG8_LDA(At, 1, 1); PG8_STAGE(PG8_SB(1, 0), b3, voffB); PG8_STAGE(PG8_SB(1, 1), b3 + hstepB, voffB); PG8_STAGE(PG8_SA(1, 0), a3, voffA);
;             PG8_WAIT_V(8); PG8_WAIT_L(0); PG8_BAR; PG8_MMA(1, 0, At, B0); PG8_MMA(1, 1, At, B1); PG8_BAR; PG8_SCHED;
;         }
	s_add_i32 s24, 0, 0x18000
	v_add_u32_e32 v136, s24, v139
	s_add_i32 s25, 0, 0x1c000
	ds_read_b128 v[150:153], v136
	ds_read_b128 v[160:163], v136 offset:1024
	ds_read_b128 v[164:167], v136 offset:2048
	ds_read_b128 v[168:171], v136 offset:3072
	v_add_u32_e32 v136, s25, v139
	ds_read_b128 v[172:175], v136
	ds_read_b128 v[176:179], v136 offset:1024
	ds_read_b128 v[180:183], v136 offset:2048
	ds_read_b128 v[184:187], v136 offset:3072
	s_add_u32 s10, s58, 0x80000
	s_addc_u32 s11, s59, 0
	s_mov_b32 m0, s15
	s_nop 0
	global_load_lds_dwordx4 v128, s[10:11]
	s_mov_b32 m0, s26
	s_nop 0
	global_load_lds_dwordx4 v132, s[10:11]
	ds_read_b128 v[188:191], v159 offset:32768
	ds_read_b128 v[192:195], v159 offset:33792
	ds_read_b128 v[196:199], v159 offset:34816
	ds_read_b128 v[200:203], v159 offset:35840
	ds_read_b128 v[204:207], v159 offset:36864
	ds_read_b128 v[208:211], v159 offset:37888
	ds_read_b128 v[212:215], v159 offset:38912
	ds_read_b128 v[216:219], v159 offset:39936
	s_waitcnt vmcnt(8)
	s_waitcnt lgkmcnt(0)
	s_barrier
	s_setprio 1
	v_mfma_f32_16x16x32_bf16 v[124:127], v[150:153], v[188:191], v[124:127]
	v_mfma_f32_16x16x32_bf16 v[120:123], v[164:167], v[188:191], v[120:123]
	v_mfma_f32_16x16x32_bf16 v[116:119], v[150:153], v[196:199], v[116:119]
	v_mfma_f32_16x16x32_bf16 v[112:115], v[164:167], v[196:199], v[112:115]
	v_mfma_f32_16x16x32_bf16 v[108:111], v[150:153], v[204:207], v[108:111]
	v_mfma_f32_16x16x32_bf16 v[104:107], v[164:167], v[204:207], v[104:107]
	v_mfma_f32_16x16x32_bf16 v[100:103], v[150:153], v[212:215], v[100:103]
	v_mfma_f32_16x16x32_bf16 v[96:99], v[164:167], v[212:215], v[96:99]
	v_mfma_f32_16x16x32_bf16 v[124:127], v[160:163], v[192:195], v[124:127]
	v_mfma_f32_16x16x32_bf16 v[120:123], v[168:171], v[192:195], v[120:123]
	v_mfma_f32_16x16x32_bf16 v[116:119], v[160:163], v[200:203], v[116:119]
	v_mfma_f32_16x16x32_bf16 v[112:115], v[168:171], v[200:203], v[112:115]
	v_mfma_f32_16x16x32_bf16 v[108:111], v[160:163], v[208:211], v[108:111]
	v_mfma_f32_16x16x32_bf16 v[104:107], v[168:171], v[208:211], v[104:107]
	v_mfma_f32_16x16x32_bf16 v[100:103], v[160:163], v[216:219], v[100:103]
	v_mfma_f32_16x16x32_bf16 v[96:99], v[168:171], v[216:219], v[96:99]
	v_mfma_f32_16x16x32_bf16 v[60:63], v[172:175], v[188:191], v[60:63]
	v_mfma_f32_16x16x32_bf16 v[56:59], v[180:183], v[188:191], v[56:59]
	v_mfma_f32_16x16x32_bf16 v[52:55], v[172:175], v[196:199], v[52:55]
	v_mfma_f32_16x16x32_bf16 v[48:51], v[180:183], v[196:199], v[48:51]
	v_mfma_f32_16x16x32_bf16 v[44:47], v[172:175], v[204:207], v[44:47]
	v_mfma_f32_16x16x32_bf16 v[40:43], v[180:183], v[204:207], v[40:43]
	v_mfma_f32_16x16x32_bf16 v[36:39], v[172:175], v[212:215], v[36:39]
	v_mfma_f32_16x16x32_bf16 v[32:35], v[180:183], v[212:215], v[32:35]
	v_mfma_f32_16x16x32_bf16 v[60:63], v[176:179], v[192:195], v[60:63]
	v_mfma_f32_16x16x32_bf16 v[56:59], v[184:187], v[192:195], v[56:59]
	v_mfma_f32_16x16x32_bf16 v[52:55], v[176:179], v[200:203], v[52:55]
	v_mfma_f32_16x16x32_bf16 v[48:51], v[184:187], v[200:203], v[48:51]
	v_mfma_f32_16x16x32_bf16 v[44:47], v[176:179], v[208:211], v[44:47]
	v_mfma_f32_16x16x32_bf16 v[40:43], v[184:187], v[208:211], v[40:43]
	v_mfma_f32_16x16x32_bf16 v[36:39], v[176:179], v[216:219], v[36:39]
	v_mfma_f32_16x16x32_bf16 v[32:35], v[184:187], v[216:219], v[32:35]
	s_setprio 0
	s_barrier
	s_add_i32 s10, s24, s94
	s_add_u32 s98, s56, 0x80
	s_addc_u32 s99, s57, 0
	s_mov_b32 m0, s10
	s_nop 0
	global_load_lds_dwordx4 v130, s[98:99]
	s_add_i32 m0, s10, 0x2000
	s_add_u32 s10, s56, 0x80080
	s_addc_u32 s11, s57, 0
	s_add_i32 s24, s25, s94
	global_load_lds_dwordx4 v134, s[98:99]
	s_mov_b32 m0, s24
	s_nop 0
	global_load_lds_dwordx4 v130, s[10:11]
	s_add_i32 m0, s24, 0x2000
	s_nop 0
	global_load_lds_dwordx4 v134, s[10:11]
	s_add_u32 s100, s58, 0x80
	s_addc_u32 s101, s59, 0
	s_mov_b32 m0, s66
	s_nop 0
	global_load_lds_dwordx4 v128, s[100:101]
	s_mov_b32 m0, s67
	s_nop 0
	global_load_lds_dwordx4 v132, s[100:101]
	ds_read_b128 v[188:191], v159 offset:49152
	ds_read_b128 v[192:195], v159 offset:50176
	ds_read_b128 v[196:199], v159 offset:51200
	ds_read_b128 v[200:203], v159 offset:52224
	ds_read_b128 v[204:207], v159 offset:53248
	ds_read_b128 v[208:211], v159 offset:54272
	ds_read_b128 v[212:215], v159 offset:55296
	ds_read_b128 v[216:219], v159 offset:56320
	s_waitcnt vmcnt(8)
	s_waitcnt lgkmcnt(0)
	s_barrier
	s_setprio 1
	v_mfma_f32_16x16x32_bf16 v[92:95], v[150:153], v[188:191], v[92:95]
	v_mfma_f32_16x16x32_bf16 v[88:91], v[164:167], v[188:191], v[88:91]
	v_mfma_f32_16x16x32_bf16 v[84:87], v[150:153], v[196:199], v[84:87]
	v_mfma_f32_16x16x32_bf16 v[80:83], v[164:167], v[196:199], v[80:83]
	v_mfma_f32_16x16x32_bf16 v[76:79], v[150:153], v[204:207], v[76:79]
	v_mfma_f32_16x16x32_bf16 v[72:75], v[164:167], v[204:207], v[72:75]
	v_mfma_f32_16x16x32_bf16 v[68:71], v[150:153], v[212:215], v[68:71]
	v_mfma_f32_16x16x32_bf16 v[64:67], v[164:167], v[212:215], v[64:67]
	v_mfma_f32_16x16x32_bf16 v[92:95], v[160:163], v[192:195], v[92:95]
	v_mfma_f32_16x16x32_bf16 v[88:91], v[168:171], v[192:195], v[88:91]
	v_mfma_f32_16x16x32_bf16 v[84:87], v[160:163], v[200:203], v[84:87]
	v_mfma_f32_16x16x32_bf16 v[80:83], v[168:171], v[200:203], v[80:83]
	v_mfma_f32_16x16x32_bf16 v[76:79], v[160:163], v[208:211], v[76:79]
	v_mfma_f32_16x16x32_bf16 v[72:75], v[168:171], v[208:211], v[72:75]
	v_mfma_f32_16x16x32_bf16 v[68:71], v[160:163], v[216:219], v[68:71]
	v_mfma_f32_16x16x32_bf16 v[64:67], v[168:171], v[216:219], v[64:67]
	v_mfma_f32_16x16x32_bf16 v[28:31], v[172:175], v[188:191], v[28:31]
	v_mfma_f32_16x16x32_bf16 v[24:27], v[180:183], v[188:191], v[24:27]
	v_mfma_f32_16x16x32_bf16 v[20:23], v[172:175], v[196:199], v[20:23]
	v_mfma_f32_16x16x32_bf16 v[16:19], v[180:183], v[196:199], v[16:19]
	v_mfma_f32_16x16x32_bf16 v[12:15], v[172:175], v[204:207], v[12:15]
	v_mfma_f32_16x16x32_bf16 v[8:11], v[180:183], v[204:207], v[8:11]
	v_mfma_f32_16x16x32_bf16 v[4:7], v[172:175], v[212:215], v[4:7]
	v_mfma_f32_16x16x32_bf16 v[0:3], v[180:183], v[212:215], v[0:3]
	v_mfma_f32_16x16x32_bf16 v[28:31], v[176:179], v[192:195], v[28:31]
	v_mfma_f32_16x16x32_bf16 v[24:27], v[184:187], v[192:195], v[24:27]
	v_mfma_f32_16x16x32_bf16 v[20:23], v[176:179], v[200:203], v[20:23]
	v_mfma_f32_16x16x32_bf16 v[16:19], v[184:187], v[200:203], v[16:19]
	v_mfma_f32_16x16x32_bf16 v[12:15], v[176:179], v[208:211], v[12:15]
	v_mfma_f32_16x16x32_bf16 v[8:11], v[184:187], v[208:211], v[8:11]
	v_mfma_f32_16x16x32_bf16 v[4:7], v[176:179], v[216:219], v[4:7]
	v_mfma_f32_16x16x32_bf16 v[0:3], v[184:187], v[216:219], v[0:3]
	s_setprio 0
	s_barrier
	s_add_i32 s60, s60, 2
	s_add_u32 s49, s49, 0x100
	s_addc_u32 s55, s55, 0
	s_cmp_gt_u32 s60, 29
	s_mov_b64 s[10:11], s[8:9]
	s_cbranch_scc0 .LBB0_157
	s_and_b64 vcc, exec, s[22:23]
	s_cbranch_vccz .LBB0_160
	s_barrier

; #define PG8_STAGE(bufoff, gbase, voff) do { _Pragma("unroll") for (int _i = 0; _i < 2; ++_i) \
;         __builtin_amdgcn_global_load_lds((const unsigned*)((const char*)(gbase) + (voff)[_i]), (LAS unsigned*)(lds + (bufoff) + ldsw + _i * 8192), 16, 0, 0); } while (0)
; #define PG8_LDA(dst, b, h) do { _Pragma("unroll") for (int m = 0; m < 4; ++m) _Pragma("unroll") for (int k = 0; k < 2; ++k) dst[m][k] = *(const LAS bf16x8*)(lds + PG8_SA(b, h) + aoff + m * 2048 + k * 1024); } while (0)
; #define PG8_LDB(dst, b, h) do { _Pragma("unroll") for (int n = 0; n < 2; ++n) _Pragma("unroll") for (int k = 0; k < 2; ++k) dst[n][k] = *(const LAS bf16x8*)(lds + PG8_SB(b, h) + boff + n * 2048 + k * 1024); } while (0)
; #define PG8_MMA(ai, bj, At, Bt) do { __builtin_amdgcn_s_setprio(1); _Pragma("unroll") for (int m = 0; m < 4; ++m) _Pragma("unroll") for (int n = 0; n < 2; ++n) _Pragma("unroll") for (int k = 0; k < 2; ++k) \
;         acc[ai][bj][m][n] = __builtin_amdgcn_mfma_f32_16x16x32_bf16(Bt[n][k], At[m][k], acc[ai][bj][m][n], 0, 0, 0); __builtin_amdgcn_s_setprio(0); } while (0)
; #define PG8_WAIT_V(n) asm volatile("s_waitcnt vmcnt(" #n ")" ::: "memory")
; #define PG8_WAIT_L(n) asm volatile("s_waitcnt lgkmcnt(" #n ")" ::: "memory")
; #define PG8_BAR __builtin_amdgcn_s_barrier()
; #define PG8_SCHED __builtin_amdgcn_sched_barrier(0)
; template <class Epi>
; __device__ __forceinline__ void gemm_phase(LAS unsigned char* lds, const Gemm g, const StaticOrder& S, const Epi& E, const int wid) {
;     ...
;         for (int t = 0; t < nt; t += 2) {
;             const bool last = (t == nt - 2);
;             const char* a1 = cA + (size_t)(t + 1) * kstep;
;             const char* a2 = last ? nA : cA + (size_t)(t + 2) * kstep; const char* b2 = last ? nB : cB + (size_t)(t + 2) * kstep;
;             const char* a3 = a2 + kstep; const char* b3 = b2 + kstep;
;             PG8_LDB(B0, 0, 0); PG8_LDB(B1, 0, 1); PG8_SCHED; PG8_LDA(At, 0, 0); PG8_STAGE(PG8_SA(1, 1), a1 + hstepA, voffA);
;             PG8_WAIT_V(8); PG8_WAIT_L(0); PG8_BAR; PG8_MMA(0, 0, At, B0); PG8_MMA(0, 1, At, B1); PG8_BAR; PG8_SCHED;
;             PG8_LDA(At, 0, 1); PG8_STAGE(PG8_SB(0, 0), b2, voffB); PG8_STAGE(PG8_SB(0, 1), b2 + hstepB, voffB); PG8_STAGE(PG8_SA(0, 0), a2, voffA);
;             PG8_WAIT_V(8); PG8_WAIT_L(0); PG8_BAR; PG8_MMA(1, 0, At, B0); PG8_MMA(1, 1, At, B1); PG8_BAR; PG8_SCHED;
.LBB0_1669:
	ds_read_b128 v[144:147], v157
	ds_read_b128 v[148:151], v157 offset:1024
	ds_read_b128 v[160:163], v157 offset:2048
	ds_read_b128 v[164:167], v157 offset:3072
	ds_read_b128 v[168:171], v158
	ds_read_b128 v[172:175], v158 offset:1024
	ds_read_b128 v[176:179], v158 offset:2048
	ds_read_b128 v[180:183], v158 offset:3072
	s_add_u32 s6, s46, 0x100
	s_addc_u32 s7, s47, 0
	s_cmp_eq_u32 s55, 12
	s_cselect_b32 s51, s43, s7
	s_cselect_b32 s50, s42, s6
	s_cselect_b32 s49, s11, s54
	s_cselect_b32 s48, s21, s53
	s_add_i32 m0, s0, 0xc000
	s_nop 0
	global_load_lds_dwordx4 v136, s[46:47]
	s_add_i32 m0, s0, 0xe000
	s_nop 0
	global_load_lds_dwordx4 v138, s[46:47]
	ds_read_b128 v[184:187], v159
	ds_read_b128 v[188:191], v159 offset:1024
	ds_read_b128 v[192:195], v159 offset:2048
	ds_read_b128 v[196:199], v159 offset:3072
	ds_read_b128 v[200:203], v159 offset:4096
	ds_read_b128 v[204:207], v159 offset:5120
	ds_read_b128 v[208:211], v159 offset:6144
	ds_read_b128 v[212:215], v159 offset:7168
	s_waitcnt vmcnt(8)
	s_waitcnt lgkmcnt(0)
	s_barrier
	s_setprio 1
	v_mfma_f32_16x16x32_bf16 v[124:127], v[144:147], v[184:187], v[124:127]
	v_mfma_f32_16x16x32_bf16 v[120:123], v[160:163], v[184:187], v[120:123]
	v_mfma_f32_16x16x32_bf16 v[116:119], v[144:147], v[192:195], v[116:119]
	v_mfma_f32_16x16x32_bf16 v[112:115], v[160:163], v[192:195], v[112:115]
	v_mfma_f32_16x16x32_bf16 v[108:111], v[144:147], v[200:203], v[108:111]
	v_mfma_f32_16x16x32_bf16 v[104:107], v[160:163], v[200:203], v[104:107]
	v_mfma_f32_16x16x32_bf16 v[100:103], v[144:147], v[208:211], v[100:103]
	v_mfma_f32_16x16x32_bf16 v[96:99], v[160:163], v[208:211], v[96:99]
	v_mfma_f32_16x16x32_bf16 v[124:127], v[148:151], v[188:191], v[124:127]
	v_mfma_f32_16x16x32_bf16 v[120:123], v[164:167], v[188:191], v[120:123]
	v_mfma_f32_16x16x32_bf16 v[116:119], v[148:151], v[196:199], v[116:119]
	v_mfma_f32_16x16x32_bf16 v[112:115], v[164:167], v[196:199], v[112:115]
	v_mfma_f32_16x16x32_bf16 v[108:111], v[148:151], v[204:207], v[108:111]
	v_mfma_f32_16x16x32_bf16 v[104:107], v[164:167], v[204:207], v[104:107]
	v_mfma_f32_16x16x32_bf16 v[100:103], v[148:151], v[212:215], v[100:103]
	v_mfma_f32_16x16x32_bf16 v[96:99], v[164:167], v[212:215], v[96:99]
	v_mfma_f32_16x16x32_bf16 v[68:71], v[168:171], v[184:187], v[68:71]
	v_mfma_f32_16x16x32_bf16 v[60:63], v[176:179], v[184:187], v[60:63]
	v_mfma_f32_16x16x32_bf16 v[52:55], v[168:171], v[192:195], v[52:55]
	v_mfma_f32_16x16x32_bf16 v[48:51], v[176:179], v[192:195], v[48:51]
	v_mfma_f32_16x16x32_bf16 v[44:47], v[168:171], v[200:203], v[44:47]
	v_mfma_f32_16x16x32_bf16 v[40:43], v[176:179], v[200:203], v[40:43]
	v_mfma_f32_16x16x32_bf16 v[36:39], v[168:171], v[208:211], v[36:39]
	v_mfma_f32_16x16x32_bf16 v[32:35], v[176:179], v[208:211], v[32:35]
	v_mfma_f32_16x16x32_bf16 v[68:71], v[172:175], v[188:191], v[68:71]
	v_mfma_f32_16x16x32_bf16 v[60:63], v[180:183], v[188:191], v[60:63]
	v_mfma_f32_16x16x32_bf16 v[52:55], v[172:175], v[196:199], v[52:55]
	v_mfma_f32_16x16x32_bf16 v[48:51], v[180:183], v[196:199], v[48:51]
	v_mfma_f32_16x16x32_bf16 v[44:47], v[172:175], v[204:207], v[44:47]
	v_mfma_f32_16x16x32_bf16 v[40:43], v[180:183], v[204:207], v[40:43]
	v_mfma_f32_16x16x32_bf16 v[36:39], v[172:175], v[212:215], v[36:39]
	v_mfma_f32_16x16x32_bf16 v[32:35], v[180:183], v[212:215], v[32:35]
	s_setprio 0
	s_barrier
	s_add_i32 s24, s36, s94
	s_mov_b32 m0, s24
	s_nop 0
	global_load_lds_dwordx4 v132, s[48:49]
	s_add_i32 m0, s24, 0x2000
	s_add_u32 s24, s48, 0x40000
	s_addc_u32 s25, s49, 0
	s_add_i32 s46, s37, s94
	global_load_lds_dwordx4 v128, s[48:49]
	s_mov_b32 m0, s46
	s_nop 0
	global_load_lds_dwordx4 v132, s[24:25]
	s_add_i32 m0, s46, 0x2000
	s_nop 0
	global_load_lds_dwordx4 v128, s[24:25]
	s_mov_b32 m0, s0
	s_nop 0
	global_load_lds_dwordx4 v134, s[50:51]
	s_mov_b32 m0, s1
	s_nop 0
	global_load_lds_dwordx4 v130, s[50:51]
	ds_read_b128 v[184:187], v159 offset:16384
	ds_read_b128 v[188:191], v159 offset:17408
	ds_read_b128 v[192:195], v159 offset:18432
	ds_read_b128 v[196:199], v159 offset:19456
	ds_read_b128 v[200:203], v159 offset:20480
	ds_read_b128 v[204:207], v159 offset:21504
	ds_read_b128 v[208:211], v159 offset:22528
	ds_read_b128 v[212:215], v159 offset:23552
	s_waitcnt vmcnt(8)
	s_waitcnt lgkmcnt(0)
	s_barrier
	s_setprio 1
	v_mfma_f32_16x16x32_bf16 v[92:95], v[144:147], v[184:187], v[92:95]
	v_mfma_f32_16x16x32_bf16 v[88:91], v[160:163], v[184:187], v[88:91]
	v_mfma_f32_16x16x32_bf16 v[84:87], v[144:147], v[192:195], v[84:87]
	v_mfma_f32_16x16x32_bf16 v[80:83], v[160:163], v[192:195], v[80:83]
	v_mfma_f32_16x16x32_bf16 v[76:79], v[144:147], v[200:203], v[76:79]
	v_mfma_f32_16x16x32_bf16 v[72:75], v[160:163], v[200:203], v[72:75]
	v_mfma_f32_16x16x32_bf16 v[64:67], v[144:147], v[208:211], v[64:67]
	v_mfma_f32_16x16x32_bf16 v[56:59], v[160:163], v[208:211], v[56:59]
	v_mfma_f32_16x16x32_bf16 v[92:95], v[148:151], v[188:191], v[92:95]
	v_mfma_f32_16x16x32_bf16 v[88:91], v[164:167], v[188:191], v[88:91]
	v_mfma_f32_16x16x32_bf16 v[84:87], v[148:151], v[196:199], v[84:87]
	v_mfma_f32_16x16x32_bf16 v[80:83], v[164:167], v[196:199], v[80:83]
	v_mfma_f32_16x16x32_bf16 v[76:79], v[148:151], v[204:207], v[76:79]
	v_mfma_f32_16x16x32_bf16 v[72:75], v[164:167], v[204:207], v[72:75]
	v_mfma_f32_16x16x32_bf16 v[64:67], v[148:151], v[212:215], v[64:67]
	v_mfma_f32_16x16x32_bf16 v[56:59], v[164:167], v[212:215], v[56:59]
	v_mfma_f32_16x16x32_bf16 v[28:31], v[168:171], v[184:187], v[28:31]
	v_mfma_f32_16x16x32_bf16 v[24:27], v[176:179], v[184:187], v[24:27]
	v_mfma_f32_16x16x32_bf16 v[20:23], v[168:171], v[192:195], v[20:23]
	v_mfma_f32_16x16x32_bf16 v[16:19], v[176:179], v[192:195], v[16:19]
	v_mfma_f32_16x16x32_bf16 v[12:15], v[168:171], v[200:203], v[12:15]
	v_mfma_f32_16x16x32_bf16 v[8:11], v[176:179], v[200:203], v[8:11]
	v_mfma_f32_16x16x32_bf16 v[4:7], v[168:171], v[208:211], v[4:7]
	v_mfma_f32_16x16x32_bf16 v[0:3], v[176:179], v[208:211], v[0:3]
	v_mfma_f32_16x16x32_bf16 v[28:31], v[172:175], v[188:191], v[28:31]
	v_mfma_f32_16x16x32_bf16 v[24:27], v[180:183], v[188:191], v[24:27]
	v_mfma_f32_16x16x32_bf16 v[20:23], v[172:175], v[196:199], v[20:23]
	v_mfma_f32_16x16x32_bf16 v[16:19], v[180:183], v[196:199], v[16:19]
	v_mfma_f32_16x16x32_bf16 v[12:15], v[172:175], v[204:207], v[12:15]
	v_mfma_f32_16x16x32_bf16 v[8:11], v[180:183], v[204:207], v[8:11]
	v_mfma_f32_16x16x32_bf16 v[4:7], v[172:175], v[212:215], v[4:7]
	v_mfma_f32_16x16x32_bf16 v[0:3], v[180:183], v[212:215], v[0:3]
	s_setprio 0
	s_barrier
; #define PG8_STAGE(bufoff, gbase, voff) do { _Pragma("unroll") for (int _i = 0; _i < 2; ++_i) \
;         __builtin_amdgcn_global_load_lds((const unsigned*)((const char*)(gbase) + (voff)[_i]), (LAS unsigned*)(lds + (bufoff) + ldsw + _i * 8192), 16, 0, 0); } while (0)
; #define PG8_LDA(dst, b, h) do { _Pragma("unroll") for (int m = 0; m < 4; ++m) _Pragma("unroll") for (int k = 0; k < 2; ++k) dst[m][k] = *(const LAS bf16x8*)(lds + PG8_SA(b, h) + aoff + m * 2048 + k * 1024); } while (0)
; #define PG8_LDB(dst, b, h) do { _Pragma("unroll") for (int n = 0; n < 2; ++n) _Pragma("unroll") for (int k = 0; k < 2; ++k) dst[n][k] = *(const LAS bf16x8*)(lds + PG8_SB(b, h) + boff + n * 2048 + k * 1024); } while (0)
; #define PG8_MMA(ai, bj, At, Bt) do { __builtin_amdgcn_s_setprio(1); _Pragma("unroll") for (int m = 0; m < 4; ++m) _Pragma("unroll") for (int n = 0; n < 2; ++n) _Pragma("unroll") for (int k = 0; k < 2; ++k) \
;         acc[ai][bj][m][n] = __builtin_amdgcn_mfma_f32_16x16x32_bf16(Bt[n][k], At[m][k], acc[ai][bj][m][n], 0, 0, 0); __builtin_amdgcn_s_setprio(0); } while (0)
; #define PG8_WAIT_V(n) asm volatile("s_waitcnt vmcnt(" #n ")" ::: "memory")
; #define PG8_WAIT_L(n) asm volatile("s_waitcnt lgkmcnt(" #n ")" ::: "memory")
; #define PG8_BAR __builtin_amdgcn_s_barrier()
; #define PG8_SCHED __builtin_amdgcn_sched_barrier(0)
; template <class Epi>
; __device__ __forceinline__ void gemm_phase(LAS unsigned char* lds, const Gemm g, const StaticOrder& S, const Epi& E, const int wid) {
;     ...
;             PG8_LDB(B0, 1, 0); PG8_LDB(B1, 1, 1); PG8_SCHED; PG8_LDA(At, 1, 0); PG8_STAGE(PG8_SA(0, 1), a2 + hstepA, voffA);
;             PG8_WAIT_V(8); PG8_WAIT_L(0); PG8_BAR; PG8_MMA(0, 0, At, B0); PG8_MMA(0, 1, At, B1); PG8_BAR; PG8_SCHED;
;             PG8_LDA(At, 1, 1); PG8_STAGE(PG8_SB(1, 0), b3, voffB); PG8_STAGE(PG8_SB(1, 1), b3 + hstepB, voffB); PG8_STAGE(PG8_SA(1, 0), a3, voffA);
;             PG8_WAIT_V(8); PG8_WAIT_L(0); PG8_BAR; PG8_MMA(1, 0, At, B0); PG8_MMA(1, 1, At, B1); PG8_BAR; PG8_SCHED;
;         }
	s_add_i32 s46, 0, 0x18000
	s_add_i32 s47, 0, 0x1c000
	v_add_u32_e32 v164, s46, v154
	v_add_u32_e32 v180, s47, v154
	ds_read_b128 v[144:147], v164
	ds_read_b128 v[148:151], v164 offset:1024
	ds_read_b128 v[160:163], v164 offset:2048
	ds_read_b128 v[164:167], v164 offset:3072
	ds_read_b128 v[168:171], v180
	ds_read_b128 v[172:175], v180 offset:1024
	ds_read_b128 v[176:179], v180 offset:2048
	ds_read_b128 v[180:183], v180 offset:3072
	s_add_u32 s24, s50, 0x40000
	s_addc_u32 s25, s51, 0
	s_mov_b32 m0, s15
	s_nop 0
	global_load_lds_dwordx4 v134, s[24:25]
	s_mov_b32 m0, s26
	s_nop 0
	global_load_lds_dwordx4 v130, s[24:25]
	ds_read_b128 v[184:187], v159 offset:32768
	ds_read_b128 v[188:191], v159 offset:33792
	ds_read_b128 v[192:195], v159 offset:34816
	ds_read_b128 v[196:199], v159 offset:35840
	ds_read_b128 v[200:203], v159 offset:36864
	ds_read_b128 v[204:207], v159 offset:37888
	ds_read_b128 v[208:211], v159 offset:38912
	ds_read_b128 v[212:215], v159 offset:39936
	s_waitcnt vmcnt(8)
	s_waitcnt lgkmcnt(0)
	s_barrier
	s_setprio 1
	v_mfma_f32_16x16x32_bf16 v[124:127], v[144:147], v[184:187], v[124:127]
	v_mfma_f32_16x16x32_bf16 v[120:123], v[160:163], v[184:187], v[120:123]
	v_mfma_f32_16x16x32_bf16 v[116:119], v[144:147], v[192:195], v[116:119]
	v_mfma_f32_16x16x32_bf16 v[112:115], v[160:163], v[192:195], v[112:115]
	v_mfma_f32_16x16x32_bf16 v[108:111], v[144:147], v[200:203], v[108:111]
	v_mfma_f32_16x16x32_bf16 v[104:107], v[160:163], v[200:203], v[104:107]
	v_mfma_f32_16x16x32_bf16 v[100:103], v[144:147], v[208:211], v[100:103]
	v_mfma_f32_16x16x32_bf16 v[96:99], v[160:163], v[208:211], v[96:99]
	v_mfma_f32_16x16x32_bf16 v[124:127], v[148:151], v[188:191], v[124:127]
	v_mfma_f32_16x16x32_bf16 v[120:123], v[164:167], v[188:191], v[120:123]
	v_mfma_f32_16x16x32_bf16 v[116:119], v[148:151], v[196:199], v[116:119]
	v_mfma_f32_16x16x32_bf16 v[112:115], v[164:167], v[196:199], v[112:115]
	v_mfma_f32_16x16x32_bf16 v[108:111], v[148:151], v[204:207], v[108:111]
	v_mfma_f32_16x16x32_bf16 v[104:107], v[164:167], v[204:207], v[104:107]
	v_mfma_f32_16x16x32_bf16 v[100:103], v[148:151], v[212:215], v[100:103]
	v_mfma_f32_16x16x32_bf16 v[96:99], v[164:167], v[212:215], v[96:99]
	v_mfma_f32_16x16x32_bf16 v[68:71], v[168:171], v[184:187], v[68:71]
	v_mfma_f32_16x16x32_bf16 v[60:63], v[176:179], v[184:187], v[60:63]
	v_mfma_f32_16x16x32_bf16 v[52:55], v[168:171], v[192:195], v[52:55]
	v_mfma_f32_16x16x32_bf16 v[48:51], v[176:179], v[192:195], v[48:51]
	v_mfma_f32_16x16x32_bf16 v[44:47], v[168:171], v[200:203], v[44:47]
	v_mfma_f32_16x16x32_bf16 v[40:43], v[176:179], v[200:203], v[40:43]
	v_mfma_f32_16x16x32_bf16 v[36:39], v[168:171], v[208:211], v[36:39]
	v_mfma_f32_16x16x32_bf16 v[32:35], v[176:179], v[208:211], v[32:35]
	v_mfma_f32_16x16x32_bf16 v[68:71], v[172:175], v[188:191], v[68:71]
	v_mfma_f32_16x16x32_bf16 v[60:63], v[180:183], v[188:191], v[60:63]
	v_mfma_f32_16x16x32_bf16 v[52:55], v[172:175], v[196:199], v[52:55]
	v_mfma_f32_16x16x32_bf16 v[48:51], v[180:183], v[196:199], v[48:51]
	v_mfma_f32_16x16x32_bf16 v[44:47], v[172:175], v[204:207], v[44:47]
	v_mfma_f32_16x16x32_bf16 v[40:43], v[180:183], v[204:207], v[40:43]
	v_mfma_f32_16x16x32_bf16 v[36:39], v[172:175], v[212:215], v[36:39]
	v_mfma_f32_16x16x32_bf16 v[32:35], v[180:183], v[212:215], v[32:35]
	s_setprio 0
	s_barrier
	s_add_i32 s24, s46, s94
	s_add_u32 s98, s48, 0x80
	s_addc_u32 s99, s49, 0
	s_mov_b32 m0, s24
	s_nop 0
	global_load_lds_dwordx4 v132, s[98:99]
	s_add_i32 m0, s24, 0x2000
	s_add_u32 s24, s48, 0x40080
	s_addc_u32 s25, s49, 0
	s_add_i32 s46, s47, s94
	global_load_lds_dwordx4 v128, s[98:99]
	s_mov_b32 m0, s46
	s_nop 0
	global_load_lds_dwordx4 v132, s[24:25]
	s_add_i32 m0, s46, 0x2000
	s_nop 0
	global_load_lds_dwordx4 v128, s[24:25]
	s_add_u32 s100, s50, 0x80
	s_addc_u32 s101, s51, 0
	s_mov_b32 m0, s28
	s_nop 0
	global_load_lds_dwordx4 v134, s[100:101]
	s_mov_b32 m0, s29
	s_nop 0
	global_load_lds_dwordx4 v130, s[100:101]
	ds_read_b128 v[184:187], v159 offset:49152
	ds_read_b128 v[188:191], v159 offset:50176
	ds_read_b128 v[192:195], v159 offset:51200
	ds_read_b128 v[196:199], v159 offset:52224
	ds_read_b128 v[200:203], v159 offset:53248
	ds_read_b128 v[204:207], v159 offset:54272
	ds_read_b128 v[208:211], v159 offset:55296
	ds_read_b128 v[212:215], v159 offset:56320
	s_waitcnt vmcnt(8)
	s_waitcnt lgkmcnt(0)
	s_barrier
	s_setprio 1
	v_mfma_f32_16x16x32_bf16 v[92:95], v[144:147], v[184:187], v[92:95]
	v_mfma_f32_16x16x32_bf16 v[88:91], v[160:163], v[184:187], v[88:91]
	v_mfma_f32_16x16x32_bf16 v[84:87], v[144:147], v[192:195], v[84:87]
	v_mfma_f32_16x16x32_bf16 v[80:83], v[160:163], v[192:195], v[80:83]
	v_mfma_f32_16x16x32_bf16 v[76:79], v[144:147], v[200:203], v[76:79]
	v_mfma_f32_16x16x32_bf16 v[72:75], v[160:163], v[200:203], v[72:75]
	v_mfma_f32_16x16x32_bf16 v[64:67], v[144:147], v[208:211], v[64:67]
	v_mfma_f32_16x16x32_bf16 v[56:59], v[160:163], v[208:211], v[56:59]
	v_mfma_f32_16x16x32_bf16 v[92:95], v[148:151], v[188:191], v[92:95]
	v_mfma_f32_16x16x32_bf16 v[88:91], v[164:167], v[188:191], v[88:91]
	v_mfma_f32_16x16x32_bf16 v[84:87], v[148:151], v[196:199], v[84:87]
	v_mfma_f32_16x16x32_bf16 v[80:83], v[164:167], v[196:199], v[80:83]
	v_mfma_f32_16x16x32_bf16 v[76:79], v[148:151], v[204:207], v[76:79]
	v_mfma_f32_16x16x32_bf16 v[72:75], v[164:167], v[204:207], v[72:75]
	v_mfma_f32_16x16x32_bf16 v[64:67], v[148:151], v[212:215], v[64:67]
	v_mfma_f32_16x16x32_bf16 v[56:59], v[164:167], v[212:215], v[56:59]
	v_mfma_f32_16x16x32_bf16 v[28:31], v[168:171], v[184:187], v[28:31]
	v_mfma_f32_16x16x32_bf16 v[24:27], v[176:179], v[184:187], v[24:27]
	v_mfma_f32_16x16x32_bf16 v[20:23], v[168:171], v[192:195], v[20:23]
	v_mfma_f32_16x16x32_bf16 v[16:19], v[176:179], v[192:195], v[16:19]
	v_mfma_f32_16x16x32_bf16 v[12:15], v[168:171], v[200:203], v[12:15]
	v_mfma_f32_16x16x32_bf16 v[8:11], v[176:179], v[200:203], v[8:11]
	v_mfma_f32_16x16x32_bf16 v[4:7], v[168:171], v[208:211], v[4:7]
	v_mfma_f32_16x16x32_bf16 v[0:3], v[176:179], v[208:211], v[0:3]
	v_mfma_f32_16x16x32_bf16 v[28:31], v[172:175], v[188:191], v[28:31]
	v_mfma_f32_16x16x32_bf16 v[24:27], v[180:183], v[188:191], v[24:27]
	v_mfma_f32_16x16x32_bf16 v[20:23], v[172:175], v[196:199], v[20:23]
	v_mfma_f32_16x16x32_bf16 v[16:19], v[180:183], v[196:199], v[16:19]
	v_mfma_f32_16x16x32_bf16 v[12:15], v[172:175], v[204:207], v[12:15]
	v_mfma_f32_16x16x32_bf16 v[8:11], v[180:183], v[204:207], v[8:11]
	v_mfma_f32_16x16x32_bf16 v[4:7], v[172:175], v[212:215], v[4:7]
	v_mfma_f32_16x16x32_bf16 v[0:3], v[180:183], v[212:215], v[0:3]
	s_setprio 0
	s_barrier
	s_add_i32 s55, s55, 2
	s_add_u32 s53, s53, 0x100
	s_addc_u32 s54, s54, 0
	s_cmp_gt_u32 s55, 13
	s_mov_b64 s[46:47], s[6:7]
	s_cbranch_scc0 .LBB0_1669
	s_and_b64 vcc, exec, s[22:23]
	s_cbranch_vccz .LBB0_1672
	s_barrier

; #define PG8_STAGE(bufoff, gbase, voff) do { _Pragma("unroll") for (int _i = 0; _i < 2; ++_i) \
;         __builtin_amdgcn_global_load_lds((const unsigned*)((const char*)(gbase) + (voff)[_i]), (LAS unsigned*)(lds + (bufoff) + ldsw + _i * 8192), 16, 0, 0); } while (0)
; #define PG8_LDA(dst, b, h) do { _Pragma("unroll") for (int m = 0; m < 4; ++m) _Pragma("unroll") for (int k = 0; k < 2; ++k) dst[m][k] = *(const LAS bf16x8*)(lds + PG8_SA(b, h) + aoff + m * 2048 + k * 1024); } while (0)
; #define PG8_LDB(dst, b, h) do { _Pragma("unroll") for (int n = 0; n < 2; ++n) _Pragma("unroll") for (int k = 0; k < 2; ++k) dst[n][k] = *(const LAS bf16x8*)(lds + PG8_SB(b, h) + boff + n * 2048 + k * 1024); } while (0)
; #define PG8_MMA(ai, bj, At, Bt) do { __builtin_amdgcn_s_setprio(1); _Pragma("unroll") for (int m = 0; m < 4; ++m) _Pragma("unroll") for (int n = 0; n < 2; ++n) _Pragma("unroll") for (int k = 0; k < 2; ++k) \
;         acc[ai][bj][m][n] = __builtin_amdgcn_mfma_f32_16x16x32_bf16(Bt[n][k], At[m][k], acc[ai][bj][m][n], 0, 0, 0); __builtin_amdgcn_s_setprio(0); } while (0)
; #define PG8_WAIT_V(n) asm volatile("s_waitcnt vmcnt(" #n ")" ::: "memory")
; #define PG8_WAIT_L(n) asm volatile("s_waitcnt lgkmcnt(" #n ")" ::: "memory")
; #define PG8_BAR __builtin_amdgcn_s_barrier()
; #define PG8_SCHED __builtin_amdgcn_sched_barrier(0)
; template <class Epi>
; __device__ __forceinline__ void gemm_phase(LAS unsigned char* lds, const Gemm g, const StaticOrder& S, const Epi& E, const int wid) {
;     ...
;         for (int t = 0; t < nt; t += 2) {
;             const bool last = (t == nt - 2);
;             const char* a1 = cA + (size_t)(t + 1) * kstep;
;             const char* a2 = last ? nA : cA + (size_t)(t + 2) * kstep; const char* b2 = last ? nB : cB + (size_t)(t + 2) * kstep;
;             const char* a3 = a2 + kstep; const char* b3 = b2 + kstep;
;             PG8_LDB(B0, 0, 0); PG8_LDB(B1, 0, 1); PG8_SCHED; PG8_LDA(At, 0, 0); PG8_STAGE(PG8_SA(1, 1), a1 + hstepA, voffA);
;             PG8_WAIT_V(8); PG8_WAIT_L(0); PG8_BAR; PG8_MMA(0, 0, At, B0); PG8_MMA(0, 1, At, B1); PG8_BAR; PG8_SCHED;
;             PG8_LDA(At, 0, 1); PG8_STAGE(PG8_SB(0, 0), b2, voffB); PG8_STAGE(PG8_SB(0, 1), b2 + hstepB, voffB); PG8_STAGE(PG8_SA(0, 0), a2, voffA);
;             PG8_WAIT_V(8); PG8_WAIT_L(0); PG8_BAR; PG8_MMA(1, 0, At, B0); PG8_MMA(1, 1, At, B1); PG8_BAR; PG8_SCHED;
.LBB0_1692:
	ds_read_b128 v[144:147], v159
	ds_read_b128 v[148:151], v159 offset:1024
	ds_read_b128 v[152:155], v159 offset:2048
	ds_read_b128 v[162:165], v159 offset:3072
	ds_read_b128 v[166:169], v160
	ds_read_b128 v[170:173], v160 offset:1024
	ds_read_b128 v[174:177], v160 offset:2048
	ds_read_b128 v[178:181], v160 offset:3072
	s_add_u32 s6, s50, 0x100
	s_addc_u32 s7, s51, 0
	s_cmp_eq_u32 s58, 12
	s_cselect_b32 s55, s47, s7
	s_cselect_b32 s54, s46, s6
	s_cselect_b32 s53, s21, s57
	s_cselect_b32 s52, s38, s45
	s_add_i32 m0, s0, 0xc000
	s_nop 0
	global_load_lds_dwordx4 v136, s[50:51]
	s_add_i32 m0, s0, 0xe000
	s_nop 0
	global_load_lds_dwordx4 v138, s[50:51]
	ds_read_b128 v[182:185], v161
	ds_read_b128 v[186:189], v161 offset:1024
	ds_read_b128 v[190:193], v161 offset:2048
	ds_read_b128 v[194:197], v161 offset:3072
	ds_read_b128 v[198:201], v161 offset:4096
	ds_read_b128 v[202:205], v161 offset:5120
	ds_read_b128 v[206:209], v161 offset:6144
	ds_read_b128 v[210:213], v161 offset:7168
	s_waitcnt vmcnt(8)
	s_waitcnt lgkmcnt(0)
	s_barrier
	s_setprio 1
	v_mfma_f32_16x16x32_bf16 v[124:127], v[144:147], v[182:185], v[124:127]
	v_mfma_f32_16x16x32_bf16 v[120:123], v[152:155], v[182:185], v[120:123]
	v_mfma_f32_16x16x32_bf16 v[116:119], v[144:147], v[190:193], v[116:119]
	v_mfma_f32_16x16x32_bf16 v[112:115], v[152:155], v[190:193], v[112:115]
	v_mfma_f32_16x16x32_bf16 v[108:111], v[144:147], v[198:201], v[108:111]
	v_mfma_f32_16x16x32_bf16 v[104:107], v[152:155], v[198:201], v[104:107]
	v_mfma_f32_16x16x32_bf16 v[100:103], v[144:147], v[206:209], v[100:103]
	v_mfma_f32_16x16x32_bf16 v[96:99], v[152:155], v[206:209], v[96:99]
	v_mfma_f32_16x16x32_bf16 v[124:127], v[148:151], v[186:189], v[124:127]
	v_mfma_f32_16x16x32_bf16 v[120:123], v[162:165], v[186:189], v[120:123]
	v_mfma_f32_16x16x32_bf16 v[116:119], v[148:151], v[194:197], v[116:119]
	v_mfma_f32_16x16x32_bf16 v[112:115], v[162:165], v[194:197], v[112:115]
	v_mfma_f32_16x16x32_bf16 v[108:111], v[148:151], v[202:205], v[108:111]
	v_mfma_f32_16x16x32_bf16 v[104:107], v[162:165], v[202:205], v[104:107]
	v_mfma_f32_16x16x32_bf16 v[100:103], v[148:151], v[210:213], v[100:103]
	v_mfma_f32_16x16x32_bf16 v[96:99], v[162:165], v[210:213], v[96:99]
	v_mfma_f32_16x16x32_bf16 v[60:63], v[166:169], v[182:185], v[60:63]
	v_mfma_f32_16x16x32_bf16 v[56:59], v[174:177], v[182:185], v[56:59]
	v_mfma_f32_16x16x32_bf16 v[52:55], v[166:169], v[190:193], v[52:55]
	v_mfma_f32_16x16x32_bf16 v[48:51], v[174:177], v[190:193], v[48:51]
	v_mfma_f32_16x16x32_bf16 v[44:47], v[166:169], v[198:201], v[44:47]
	v_mfma_f32_16x16x32_bf16 v[40:43], v[174:177], v[198:201], v[40:43]
	v_mfma_f32_16x16x32_bf16 v[36:39], v[166:169], v[206:209], v[36:39]
	v_mfma_f32_16x16x32_bf16 v[32:35], v[174:177], v[206:209], v[32:35]
	v_mfma_f32_16x16x32_bf16 v[60:63], v[170:173], v[186:189], v[60:63]
	v_mfma_f32_16x16x32_bf16 v[56:59], v[178:181], v[186:189], v[56:59]
	v_mfma_f32_16x16x32_bf16 v[52:55], v[170:173], v[194:197], v[52:55]
	v_mfma_f32_16x16x32_bf16 v[48:51], v[178:181], v[194:197], v[48:51]
	v_mfma_f32_16x16x32_bf16 v[44:47], v[170:173], v[202:205], v[44:47]
	v_mfma_f32_16x16x32_bf16 v[40:43], v[178:181], v[202:205], v[40:43]
	v_mfma_f32_16x16x32_bf16 v[36:39], v[170:173], v[210:213], v[36:39]
	v_mfma_f32_16x16x32_bf16 v[32:35], v[178:181], v[210:213], v[32:35]
	s_setprio 0
	s_barrier
	s_add_i32 s24, s34, s94
	s_mov_b32 m0, s24
	s_nop 0
	global_load_lds_dwordx4 v132, s[52:53]
	s_add_i32 m0, s24, 0x2000
	s_add_u32 s24, s52, 0x40000
	s_addc_u32 s25, s53, 0
	s_add_i32 s50, s35, s94
	global_load_lds_dwordx4 v128, s[52:53]
	s_mov_b32 m0, s50
	s_nop 0
	global_load_lds_dwordx4 v132, s[24:25]
	s_add_i32 m0, s50, 0x2000
	s_nop 0
	global_load_lds_dwordx4 v128, s[24:25]
	s_mov_b32 m0, s0
	s_nop 0
	global_load_lds_dwordx4 v134, s[54:55]
	s_mov_b32 m0, s1
	s_nop 0
	global_load_lds_dwordx4 v130, s[54:55]
	ds_read_b128 v[182:185], v161 offset:16384
	ds_read_b128 v[186:189], v161 offset:17408
	ds_read_b128 v[190:193], v161 offset:18432
	ds_read_b128 v[194:197], v161 offset:19456
	ds_read_b128 v[198:201], v161 offset:20480
	ds_read_b128 v[202:205], v161 offset:21504
	ds_read_b128 v[206:209], v161 offset:22528
	ds_read_b128 v[210:213], v161 offset:23552
	s_waitcnt vmcnt(8)
	s_waitcnt lgkmcnt(0)
	s_barrier
	s_setprio 1
	v_mfma_f32_16x16x32_bf16 v[92:95], v[144:147], v[182:185], v[92:95]
	v_mfma_f32_16x16x32_bf16 v[88:91], v[152:155], v[182:185], v[88:91]
	v_mfma_f32_16x16x32_bf16 v[84:87], v[144:147], v[190:193], v[84:87]
	v_mfma_f32_16x16x32_bf16 v[80:83], v[152:155], v[190:193], v[80:83]
	v_mfma_f32_16x16x32_bf16 v[76:79], v[144:147], v[198:201], v[76:79]
	v_mfma_f32_16x16x32_bf16 v[72:75], v[152:155], v[198:201], v[72:75]
	v_mfma_f32_16x16x32_bf16 v[68:71], v[144:147], v[206:209], v[68:71]
	v_mfma_f32_16x16x32_bf16 v[64:67], v[152:155], v[206:209], v[64:67]
	v_mfma_f32_16x16x32_bf16 v[92:95], v[148:151], v[186:189], v[92:95]
	v_mfma_f32_16x16x32_bf16 v[88:91], v[162:165], v[186:189], v[88:91]
	v_mfma_f32_16x16x32_bf16 v[84:87], v[148:151], v[194:197], v[84:87]
	v_mfma_f32_16x16x32_bf16 v[80:83], v[162:165], v[194:197], v[80:83]
	v_mfma_f32_16x16x32_bf16 v[76:79], v[148:151], v[202:205], v[76:79]
	v_mfma_f32_16x16x32_bf16 v[72:75], v[162:165], v[202:205], v[72:75]
	v_mfma_f32_16x16x32_bf16 v[68:71], v[148:151], v[210:213], v[68:71]
	v_mfma_f32_16x16x32_bf16 v[64:67], v[162:165], v[210:213], v[64:67]
	v_mfma_f32_16x16x32_bf16 v[28:31], v[166:169], v[182:185], v[28:31]
	v_mfma_f32_16x16x32_bf16 v[24:27], v[174:177], v[182:185], v[24:27]
	v_mfma_f32_16x16x32_bf16 v[20:23], v[166:169], v[190:193], v[20:23]
	v_mfma_f32_16x16x32_bf16 v[16:19], v[174:177], v[190:193], v[16:19]
	v_mfma_f32_16x16x32_bf16 v[12:15], v[166:169], v[198:201], v[12:15]
	v_mfma_f32_16x16x32_bf16 v[8:11], v[174:177], v[198:201], v[8:11]
	v_mfma_f32_16x16x32_bf16 v[4:7], v[166:169], v[206:209], v[4:7]
	v_mfma_f32_16x16x32_bf16 v[0:3], v[174:177], v[206:209], v[0:3]
	v_mfma_f32_16x16x32_bf16 v[28:31], v[170:173], v[186:189], v[28:31]
	v_mfma_f32_16x16x32_bf16 v[24:27], v[178:181], v[186:189], v[24:27]
	v_mfma_f32_16x16x32_bf16 v[20:23], v[170:173], v[194:197], v[20:23]
	v_mfma_f32_16x16x32_bf16 v[16:19], v[178:181], v[194:197], v[16:19]
	v_mfma_f32_16x16x32_bf16 v[12:15], v[170:173], v[202:205], v[12:15]
	v_mfma_f32_16x16x32_bf16 v[8:11], v[178:181], v[202:205], v[8:11]
	v_mfma_f32_16x16x32_bf16 v[4:7], v[170:173], v[210:213], v[4:7]
	v_mfma_f32_16x16x32_bf16 v[0:3], v[178:181], v[210:213], v[0:3]
	s_setprio 0
	s_barrier
; #define PG8_STAGE(bufoff, gbase, voff) do { _Pragma("unroll") for (int _i = 0; _i < 2; ++_i) \
;         __builtin_amdgcn_global_load_lds((const unsigned*)((const char*)(gbase) + (voff)[_i]), (LAS unsigned*)(lds + (bufoff) + ldsw + _i * 8192), 16, 0, 0); } while (0)
; #define PG8_LDA(dst, b, h) do { _Pragma("unroll") for (int m = 0; m < 4; ++m) _Pragma("unroll") for (int k = 0; k < 2; ++k) dst[m][k] = *(const LAS bf16x8*)(lds + PG8_SA(b, h) + aoff + m * 2048 + k * 1024); } while (0)
; #define PG8_LDB(dst, b, h) do { _Pragma("unroll") for (int n = 0; n < 2; ++n) _Pragma("unroll") for (int k = 0; k < 2; ++k) dst[n][k] = *(const LAS bf16x8*)(lds + PG8_SB(b, h) + boff + n * 2048 + k * 1024); } while (0)
; #define PG8_MMA(ai, bj, At, Bt) do { __builtin_amdgcn_s_setprio(1); _Pragma("unroll") for (int m = 0; m < 4; ++m) _Pragma("unroll") for (int n = 0; n < 2; ++n) _Pragma("unroll") for (int k = 0; k < 2; ++k) \
;         acc[ai][bj][m][n] = __builtin_amdgcn_mfma_f32_16x16x32_bf16(Bt[n][k], At[m][k], acc[ai][bj][m][n], 0, 0, 0); __builtin_amdgcn_s_setprio(0); } while (0)
; #define PG8_WAIT_V(n) asm volatile("s_waitcnt vmcnt(" #n ")" ::: "memory")
; #define PG8_WAIT_L(n) asm volatile("s_waitcnt lgkmcnt(" #n ")" ::: "memory")
; #define PG8_BAR __builtin_amdgcn_s_barrier()
; #define PG8_SCHED __builtin_amdgcn_sched_barrier(0)
; template <class Epi>
; __device__ __forceinline__ void gemm_phase(LAS unsigned char* lds, const Gemm g, const StaticOrder& S, const Epi& E, const int wid) {
;     ...
;             PG8_LDB(B0, 1, 0); PG8_LDB(B1, 1, 1); PG8_SCHED; PG8_LDA(At, 1, 0); PG8_STAGE(PG8_SA(0, 1), a2 + hstepA, voffA);
;             PG8_WAIT_V(8); PG8_WAIT_L(0); PG8_BAR; PG8_MMA(0, 0, At, B0); PG8_MMA(0, 1, At, B1); PG8_BAR; PG8_SCHED;
;             PG8_LDA(At, 1, 1); PG8_STAGE(PG8_SB(1, 0), b3, voffB); PG8_STAGE(PG8_SB(1, 1), b3 + hstepB, voffB); PG8_STAGE(PG8_SA(1, 0), a3, voffA);
;             PG8_WAIT_V(8); PG8_WAIT_L(0); PG8_BAR; PG8_MMA(1, 0, At, B0); PG8_MMA(1, 1, At, B1); PG8_BAR; PG8_SCHED;
;         }
	s_add_i32 s50, 0, 0x18000
	s_add_i32 s51, 0, 0x1c000
	v_add_u32_e32 v162, s50, v156
	v_add_u32_e32 v178, s51, v156
	ds_read_b128 v[144:147], v162
	ds_read_b128 v[148:151], v162 offset:1024
	ds_read_b128 v[152:155], v162 offset:2048
	ds_read_b128 v[162:165], v162 offset:3072
	ds_read_b128 v[166:169], v178
	ds_read_b128 v[170:173], v178 offset:1024
	ds_read_b128 v[174:177], v178 offset:2048
	ds_read_b128 v[178:181], v178 offset:3072
	s_add_u32 s24, s54, 0x40000
	s_addc_u32 s25, s55, 0
	s_mov_b32 m0, s15
	s_nop 0
	global_load_lds_dwordx4 v134, s[24:25]
	s_mov_b32 m0, s26
	s_nop 0
	global_load_lds_dwordx4 v130, s[24:25]
	ds_read_b128 v[182:185], v161 offset:32768
	ds_read_b128 v[186:189], v161 offset:33792
	ds_read_b128 v[190:193], v161 offset:34816
	ds_read_b128 v[194:197], v161 offset:35840
	ds_read_b128 v[198:201], v161 offset:36864
	ds_read_b128 v[202:205], v161 offset:37888
	ds_read_b128 v[206:209], v161 offset:38912
	ds_read_b128 v[210:213], v161 offset:39936
	s_waitcnt vmcnt(8)
	s_waitcnt lgkmcnt(0)
	s_barrier
	s_setprio 1
	v_mfma_f32_16x16x32_bf16 v[124:127], v[144:147], v[182:185], v[124:127]
	v_mfma_f32_16x16x32_bf16 v[120:123], v[152:155], v[182:185], v[120:123]
	v_mfma_f32_16x16x32_bf16 v[116:119], v[144:147], v[190:193], v[116:119]
	v_mfma_f32_16x16x32_bf16 v[112:115], v[152:155], v[190:193], v[112:115]
	v_mfma_f32_16x16x32_bf16 v[108:111], v[144:147], v[198:201], v[108:111]
	v_mfma_f32_16x16x32_bf16 v[104:107], v[152:155], v[198:201], v[104:107]
	v_mfma_f32_16x16x32_bf16 v[100:103], v[144:147], v[206:209], v[100:103]
	v_mfma_f32_16x16x32_bf16 v[96:99], v[152:155], v[206:209], v[96:99]
	v_mfma_f32_16x16x32_bf16 v[124:127], v[148:151], v[186:189], v[124:127]
	v_mfma_f32_16x16x32_bf16 v[120:123], v[162:165], v[186:189], v[120:123]
	v_mfma_f32_16x16x32_bf16 v[116:119], v[148:151], v[194:197], v[116:119]
	v_mfma_f32_16x16x32_bf16 v[112:115], v[162:165], v[194:197], v[112:115]
	v_mfma_f32_16x16x32_bf16 v[108:111], v[148:151], v[202:205], v[108:111]
	v_mfma_f32_16x16x32_bf16 v[104:107], v[162:165], v[202:205], v[104:107]
	v_mfma_f32_16x16x32_bf16 v[100:103], v[148:151], v[210:213], v[100:103]
	v_mfma_f32_16x16x32_bf16 v[96:99], v[162:165], v[210:213], v[96:99]
	v_mfma_f32_16x16x32_bf16 v[60:63], v[166:169], v[182:185], v[60:63]
	v_mfma_f32_16x16x32_bf16 v[56:59], v[174:177], v[182:185], v[56:59]
	v_mfma_f32_16x16x32_bf16 v[52:55], v[166:169], v[190:193], v[52:55]
	v_mfma_f32_16x16x32_bf16 v[48:51], v[174:177], v[190:193], v[48:51]
	v_mfma_f32_16x16x32_bf16 v[44:47], v[166:169], v[198:201], v[44:47]
	v_mfma_f32_16x16x32_bf16 v[40:43], v[174:177], v[198:201], v[40:43]
	v_mfma_f32_16x16x32_bf16 v[36:39], v[166:169], v[206:209], v[36:39]
	v_mfma_f32_16x16x32_bf16 v[32:35], v[174:177], v[206:209], v[32:35]
	v_mfma_f32_16x16x32_bf16 v[60:63], v[170:173], v[186:189], v[60:63]
	v_mfma_f32_16x16x32_bf16 v[56:59], v[178:181], v[186:189], v[56:59]
	v_mfma_f32_16x16x32_bf16 v[52:55], v[170:173], v[194:197], v[52:55]
	v_mfma_f32_16x16x32_bf16 v[48:51], v[178:181], v[194:197], v[48:51]
	v_mfma_f32_16x16x32_bf16 v[44:47], v[170:173], v[202:205], v[44:47]
	v_mfma_f32_16x16x32_bf16 v[40:43], v[178:181], v[202:205], v[40:43]
	v_mfma_f32_16x16x32_bf16 v[36:39], v[170:173], v[210:213], v[36:39]
	v_mfma_f32_16x16x32_bf16 v[32:35], v[178:181], v[210:213], v[32:35]
	s_setprio 0
	s_barrier
	s_add_i32 s24, s50, s94
	s_add_u32 s98, s52, 0x80
	s_addc_u32 s99, s53, 0
	s_mov_b32 m0, s24
	s_nop 0
	global_load_lds_dwordx4 v132, s[98:99]
	s_add_i32 m0, s24, 0x2000
	s_add_u32 s24, s52, 0x40080
	s_addc_u32 s25, s53, 0
	s_add_i32 s50, s51, s94
	global_load_lds_dwordx4 v128, s[98:99]
	s_mov_b32 m0, s50
	s_nop 0
	global_load_lds_dwordx4 v132, s[24:25]
	s_add_i32 m0, s50, 0x2000
	s_nop 0
	global_load_lds_dwordx4 v128, s[24:25]
	s_add_u32 s100, s54, 0x80
	s_addc_u32 s101, s55, 0
	s_mov_b32 m0, s28
	s_nop 0
	global_load_lds_dwordx4 v134, s[100:101]
	s_mov_b32 m0, s29
	s_nop 0
	global_load_lds_dwordx4 v130, s[100:101]
	ds_read_b128 v[182:185], v161 offset:49152
	ds_read_b128 v[186:189], v161 offset:50176
	ds_read_b128 v[190:193], v161 offset:51200
	ds_read_b128 v[194:197], v161 offset:52224
	ds_read_b128 v[198:201], v161 offset:53248
	ds_read_b128 v[202:205], v161 offset:54272
	ds_read_b128 v[206:209], v161 offset:55296
	ds_read_b128 v[210:213], v161 offset:56320
	s_waitcnt vmcnt(8)
	s_waitcnt lgkmcnt(0)
	s_barrier
	s_setprio 1
	v_mfma_f32_16x16x32_bf16 v[92:95], v[144:147], v[182:185], v[92:95]
	v_mfma_f32_16x16x32_bf16 v[88:91], v[152:155], v[182:185], v[88:91]
	v_mfma_f32_16x16x32_bf16 v[84:87], v[144:147], v[190:193], v[84:87]
	v_mfma_f32_16x16x32_bf16 v[80:83], v[152:155], v[190:193], v[80:83]
	v_mfma_f32_16x16x32_bf16 v[76:79], v[144:147], v[198:201], v[76:79]
	v_mfma_f32_16x16x32_bf16 v[72:75], v[152:155], v[198:201], v[72:75]
	v_mfma_f32_16x16x32_bf16 v[68:71], v[144:147], v[206:209], v[68:71]
	v_mfma_f32_16x16x32_bf16 v[64:67], v[152:155], v[206:209], v[64:67]
	v_mfma_f32_16x16x32_bf16 v[92:95], v[148:151], v[186:189], v[92:95]
	v_mfma_f32_16x16x32_bf16 v[88:91], v[162:165], v[186:189], v[88:91]
	v_mfma_f32_16x16x32_bf16 v[84:87], v[148:151], v[194:197], v[84:87]
	v_mfma_f32_16x16x32_bf16 v[80:83], v[162:165], v[194:197], v[80:83]
	v_mfma_f32_16x16x32_bf16 v[76:79], v[148:151], v[202:205], v[76:79]
	v_mfma_f32_16x16x32_bf16 v[72:75], v[162:165], v[202:205], v[72:75]
	v_mfma_f32_16x16x32_bf16 v[68:71], v[148:151], v[210:213], v[68:71]
	v_mfma_f32_16x16x32_bf16 v[64:67], v[162:165], v[210:213], v[64:67]
	v_mfma_f32_16x16x32_bf16 v[28:31], v[166:169], v[182:185], v[28:31]
	v_mfma_f32_16x16x32_bf16 v[24:27], v[174:177], v[182:185], v[24:27]
	v_mfma_f32_16x16x32_bf16 v[20:23], v[166:169], v[190:193], v[20:23]
	v_mfma_f32_16x16x32_bf16 v[16:19], v[174:177], v[190:193], v[16:19]
	v_mfma_f32_16x16x32_bf16 v[12:15], v[166:169], v[198:201], v[12:15]
	v_mfma_f32_16x16x32_bf16 v[8:11], v[174:177], v[198:201], v[8:11]
	v_mfma_f32_16x16x32_bf16 v[4:7], v[166:169], v[206:209], v[4:7]
	v_mfma_f32_16x16x32_bf16 v[0:3], v[174:177], v[206:209], v[0:3]
	v_mfma_f32_16x16x32_bf16 v[28:31], v[170:173], v[186:189], v[28:31]
	v_mfma_f32_16x16x32_bf16 v[24:27], v[178:181], v[186:189], v[24:27]
	v_mfma_f32_16x16x32_bf16 v[20:23], v[170:173], v[194:197], v[20:23]
	v_mfma_f32_16x16x32_bf16 v[16:19], v[178:181], v[194:197], v[16:19]
	v_mfma_f32_16x16x32_bf16 v[12:15], v[170:173], v[202:205], v[12:15]
	v_mfma_f32_16x16x32_bf16 v[8:11], v[178:181], v[202:205], v[8:11]
	v_mfma_f32_16x16x32_bf16 v[4:7], v[170:173], v[210:213], v[4:7]
	v_mfma_f32_16x16x32_bf16 v[0:3], v[178:181], v[210:213], v[0:3]
	s_setprio 0
	s_barrier
	s_add_i32 s58, s58, 2
	s_add_u32 s45, s45, 0x100
	s_addc_u32 s57, s57, 0
	s_cmp_gt_u32 s58, 13
	s_mov_b64 s[50:51], s[6:7]
	s_cbranch_scc0 .LBB0_1692
	s_and_b64 vcc, exec, s[22:23]
	s_cbranch_vccz .LBB0_1695
	s_barrier

; #define PG8_STAGE(bufoff, gbase, voff) do { _Pragma("unroll") for (int _i = 0; _i < 2; ++_i) \
;         __builtin_amdgcn_global_load_lds((const unsigned*)((const char*)(gbase) + (voff)[_i]), (LAS unsigned*)(lds + (bufoff) + ldsw + _i * 8192), 16, 0, 0); } while (0)
; #define PG8_LDA(dst, b, h) do { _Pragma("unroll") for (int m = 0; m < 4; ++m) _Pragma("unroll") for (int k = 0; k < 2; ++k) dst[m][k] = *(const LAS bf16x8*)(lds + PG8_SA(b, h) + aoff + m * 2048 + k * 1024); } while (0)
; #define PG8_LDB(dst, b, h) do { _Pragma("unroll") for (int n = 0; n < 2; ++n) _Pragma("unroll") for (int k = 0; k < 2; ++k) dst[n][k] = *(const LAS bf16x8*)(lds + PG8_SB(b, h) + boff + n * 2048 + k * 1024); } while (0)
; #define PG8_MMA(ai, bj, At, Bt) do { __builtin_amdgcn_s_setprio(1); _Pragma("unroll") for (int m = 0; m < 4; ++m) _Pragma("unroll") for (int n = 0; n < 2; ++n) _Pragma("unroll") for (int k = 0; k < 2; ++k) \
;         acc[ai][bj][m][n] = __builtin_amdgcn_mfma_f32_16x16x32_bf16(Bt[n][k], At[m][k], acc[ai][bj][m][n], 0, 0, 0); __builtin_amdgcn_s_setprio(0); } while (0)
; #define PG8_WAIT_V(n) asm volatile("s_waitcnt vmcnt(" #n ")" ::: "memory")
; #define PG8_WAIT_L(n) asm volatile("s_waitcnt lgkmcnt(" #n ")" ::: "memory")
; #define PG8_BAR __builtin_amdgcn_s_barrier()
; #define PG8_SCHED __builtin_amdgcn_sched_barrier(0)
; template <class Epi>
; __device__ __forceinline__ void gemm_phase(LAS unsigned char* lds, const Gemm g, const StaticOrder& S, const Epi& E, const int wid) {
;     ...
;         for (int t = 0; t < nt; t += 2) {
;             const bool last = (t == nt - 2);
;             const char* a1 = cA + (size_t)(t + 1) * kstep;
;             const char* a2 = last ? nA : cA + (size_t)(t + 2) * kstep; const char* b2 = last ? nB : cB + (size_t)(t + 2) * kstep;
;             const char* a3 = a2 + kstep; const char* b3 = b2 + kstep;
;             PG8_LDB(B0, 0, 0); PG8_LDB(B1, 0, 1); PG8_SCHED; PG8_LDA(At, 0, 0); PG8_STAGE(PG8_SA(1, 1), a1 + hstepA, voffA);
;             PG8_WAIT_V(8); PG8_WAIT_L(0); PG8_BAR; PG8_MMA(0, 0, At, B0); PG8_MMA(0, 1, At, B1); PG8_BAR; PG8_SCHED;
;             PG8_LDA(At, 0, 1); PG8_STAGE(PG8_SB(0, 0), b2, voffB); PG8_STAGE(PG8_SB(0, 1), b2 + hstepB, voffB); PG8_STAGE(PG8_SA(0, 0), a2, voffA);
;             PG8_WAIT_V(8); PG8_WAIT_L(0); PG8_BAR; PG8_MMA(1, 0, At, B0); PG8_MMA(1, 1, At, B1); PG8_BAR; PG8_SCHED;
.LBB0_1727:
	ds_read_b128 v[144:147], v157
	ds_read_b128 v[148:151], v157 offset:1024
	ds_read_b128 v[160:163], v157 offset:2048
	ds_read_b128 v[164:167], v157 offset:3072
	ds_read_b128 v[168:171], v158
	ds_read_b128 v[172:175], v158 offset:1024
	ds_read_b128 v[176:179], v158 offset:2048
	ds_read_b128 v[180:183], v158 offset:3072
	s_add_u32 s6, s46, 0x100
	s_addc_u32 s7, s47, 0
	s_cmp_eq_u32 s54, 28
	s_cselect_b32 s51, s43, s7
	s_cselect_b32 s50, s42, s6
	s_cselect_b32 s49, s21, s53
	s_cselect_b32 s48, s41, s52
	s_add_i32 m0, s1, 0xc000
	s_nop 0
	global_load_lds_dwordx4 v136, s[46:47]
	s_add_i32 m0, s1, 0xe000
	s_nop 0
	global_load_lds_dwordx4 v138, s[46:47]
	ds_read_b128 v[184:187], v159
	ds_read_b128 v[188:191], v159 offset:1024
	ds_read_b128 v[192:195], v159 offset:2048
	ds_read_b128 v[196:199], v159 offset:3072
	ds_read_b128 v[200:203], v159 offset:4096
	ds_read_b128 v[204:207], v159 offset:5120
	ds_read_b128 v[208:211], v159 offset:6144
	ds_read_b128 v[212:215], v159 offset:7168
	s_waitcnt vmcnt(8)
	s_waitcnt lgkmcnt(0)
	s_barrier
	s_setprio 1
	v_mfma_f32_16x16x32_bf16 v[124:127], v[144:147], v[184:187], v[124:127]
	v_mfma_f32_16x16x32_bf16 v[120:123], v[160:163], v[184:187], v[120:123]
	v_mfma_f32_16x16x32_bf16 v[116:119], v[144:147], v[192:195], v[116:119]
	v_mfma_f32_16x16x32_bf16 v[112:115], v[160:163], v[192:195], v[112:115]
	v_mfma_f32_16x16x32_bf16 v[108:111], v[144:147], v[200:203], v[108:111]
	v_mfma_f32_16x16x32_bf16 v[104:107], v[160:163], v[200:203], v[104:107]
	v_mfma_f32_16x16x32_bf16 v[100:103], v[144:147], v[208:211], v[100:103]
	v_mfma_f32_16x16x32_bf16 v[96:99], v[160:163], v[208:211], v[96:99]
	v_mfma_f32_16x16x32_bf16 v[124:127], v[148:151], v[188:191], v[124:127]
	v_mfma_f32_16x16x32_bf16 v[120:123], v[164:167], v[188:191], v[120:123]
	v_mfma_f32_16x16x32_bf16 v[116:119], v[148:151], v[196:199], v[116:119]
	v_mfma_f32_16x16x32_bf16 v[112:115], v[164:167], v[196:199], v[112:115]
	v_mfma_f32_16x16x32_bf16 v[108:111], v[148:151], v[204:207], v[108:111]
	v_mfma_f32_16x16x32_bf16 v[104:107], v[164:167], v[204:207], v[104:107]
	v_mfma_f32_16x16x32_bf16 v[100:103], v[148:151], v[212:215], v[100:103]
	v_mfma_f32_16x16x32_bf16 v[96:99], v[164:167], v[212:215], v[96:99]
	v_mfma_f32_16x16x32_bf16 v[76:79], v[168:171], v[184:187], v[76:79]
	v_mfma_f32_16x16x32_bf16 v[64:67], v[176:179], v[184:187], v[64:67]
	v_mfma_f32_16x16x32_bf16 v[56:59], v[168:171], v[192:195], v[56:59]
	v_mfma_f32_16x16x32_bf16 v[48:51], v[176:179], v[192:195], v[48:51]
	v_mfma_f32_16x16x32_bf16 v[44:47], v[168:171], v[200:203], v[44:47]
	v_mfma_f32_16x16x32_bf16 v[40:43], v[176:179], v[200:203], v[40:43]
	v_mfma_f32_16x16x32_bf16 v[36:39], v[168:171], v[208:211], v[36:39]
	v_mfma_f32_16x16x32_bf16 v[32:35], v[176:179], v[208:211], v[32:35]
	v_mfma_f32_16x16x32_bf16 v[76:79], v[172:175], v[188:191], v[76:79]
	v_mfma_f32_16x16x32_bf16 v[64:67], v[180:183], v[188:191], v[64:67]
	v_mfma_f32_16x16x32_bf16 v[56:59], v[172:175], v[196:199], v[56:59]
	v_mfma_f32_16x16x32_bf16 v[48:51], v[180:183], v[196:199], v[48:51]
	v_mfma_f32_16x16x32_bf16 v[44:47], v[172:175], v[204:207], v[44:47]
	v_mfma_f32_16x16x32_bf16 v[40:43], v[180:183], v[204:207], v[40:43]
	v_mfma_f32_16x16x32_bf16 v[36:39], v[172:175], v[212:215], v[36:39]
	v_mfma_f32_16x16x32_bf16 v[32:35], v[180:183], v[212:215], v[32:35]
	s_setprio 0
	s_barrier
	s_add_i32 s24, s35, s94
	s_mov_b32 m0, s24
	s_nop 0
	global_load_lds_dwordx4 v132, s[48:49]
	s_add_i32 m0, s24, 0x2000
	s_add_u32 s24, s48, 0x80000
	s_addc_u32 s25, s49, 0
	s_add_i32 s46, s36, s94
	global_load_lds_dwordx4 v128, s[48:49]
	s_mov_b32 m0, s46
	s_nop 0
	global_load_lds_dwordx4 v132, s[24:25]
	s_add_i32 m0, s46, 0x2000
	s_nop 0
	global_load_lds_dwordx4 v128, s[24:25]
	s_mov_b32 m0, s1
	s_nop 0
	global_load_lds_dwordx4 v134, s[50:51]
	s_mov_b32 m0, s15
	s_nop 0
	global_load_lds_dwordx4 v130, s[50:51]
	ds_read_b128 v[184:187], v159 offset:16384
	ds_read_b128 v[188:191], v159 offset:17408
	ds_read_b128 v[192:195], v159 offset:18432
	ds_read_b128 v[196:199], v159 offset:19456
	ds_read_b128 v[200:203], v159 offset:20480
	ds_read_b128 v[204:207], v159 offset:21504
	ds_read_b128 v[208:211], v159 offset:22528
	ds_read_b128 v[212:215], v159 offset:23552
	s_waitcnt vmcnt(8)
	s_waitcnt lgkmcnt(0)
	s_barrier
	s_setprio 1
	v_mfma_f32_16x16x32_bf16 v[92:95], v[144:147], v[184:187], v[92:95]
	v_mfma_f32_16x16x32_bf16 v[88:91], v[160:163], v[184:187], v[88:91]
	v_mfma_f32_16x16x32_bf16 v[84:87], v[144:147], v[192:195], v[84:87]
	v_mfma_f32_16x16x32_bf16 v[80:83], v[160:163], v[192:195], v[80:83]
	v_mfma_f32_16x16x32_bf16 v[72:75], v[144:147], v[200:203], v[72:75]
	v_mfma_f32_16x16x32_bf16 v[68:71], v[160:163], v[200:203], v[68:71]
	v_mfma_f32_16x16x32_bf16 v[60:63], v[144:147], v[208:211], v[60:63]
	v_mfma_f32_16x16x32_bf16 v[52:55], v[160:163], v[208:211], v[52:55]
	v_mfma_f32_16x16x32_bf16 v[92:95], v[148:151], v[188:191], v[92:95]
	v_mfma_f32_16x16x32_bf16 v[88:91], v[164:167], v[188:191], v[88:91]
	v_mfma_f32_16x16x32_bf16 v[84:87], v[148:151], v[196:199], v[84:87]
	v_mfma_f32_16x16x32_bf16 v[80:83], v[164:167], v[196:199], v[80:83]
	v_mfma_f32_16x16x32_bf16 v[72:75], v[148:151], v[204:207], v[72:75]
	v_mfma_f32_16x16x32_bf16 v[68:71], v[164:167], v[204:207], v[68:71]
	v_mfma_f32_16x16x32_bf16 v[60:63], v[148:151], v[212:215], v[60:63]
	v_mfma_f32_16x16x32_bf16 v[52:55], v[164:167], v[212:215], v[52:55]
	v_mfma_f32_16x16x32_bf16 v[28:31], v[168:171], v[184:187], v[28:31]
	v_mfma_f32_16x16x32_bf16 v[24:27], v[176:179], v[184:187], v[24:27]
	v_mfma_f32_16x16x32_bf16 v[20:23], v[168:171], v[192:195], v[20:23]
	v_mfma_f32_16x16x32_bf16 v[16:19], v[176:179], v[192:195], v[16:19]
	v_mfma_f32_16x16x32_bf16 v[12:15], v[168:171], v[200:203], v[12:15]
	v_mfma_f32_16x16x32_bf16 v[8:11], v[176:179], v[200:203], v[8:11]
	v_mfma_f32_16x16x32_bf16 v[4:7], v[168:171], v[208:211], v[4:7]
	v_mfma_f32_16x16x32_bf16 v[0:3], v[176:179], v[208:211], v[0:3]
	v_mfma_f32_16x16x32_bf16 v[28:31], v[172:175], v[188:191], v[28:31]
	v_mfma_f32_16x16x32_bf16 v[24:27], v[180:183], v[188:191], v[24:27]
	v_mfma_f32_16x16x32_bf16 v[20:23], v[172:175], v[196:199], v[20:23]
	v_mfma_f32_16x16x32_bf16 v[16:19], v[180:183], v[196:199], v[16:19]
	v_mfma_f32_16x16x32_bf16 v[12:15], v[172:175], v[204:207], v[12:15]
	v_mfma_f32_16x16x32_bf16 v[8:11], v[180:183], v[204:207], v[8:11]
	v_mfma_f32_16x16x32_bf16 v[4:7], v[172:175], v[212:215], v[4:7]
	v_mfma_f32_16x16x32_bf16 v[0:3], v[180:183], v[212:215], v[0:3]
	s_setprio 0
	s_barrier
; #define PG8_STAGE(bufoff, gbase, voff) do { _Pragma("unroll") for (int _i = 0; _i < 2; ++_i) \
;         __builtin_amdgcn_global_load_lds((const unsigned*)((const char*)(gbase) + (voff)[_i]), (LAS unsigned*)(lds + (bufoff) + ldsw + _i * 8192), 16, 0, 0); } while (0)
; #define PG8_LDA(dst, b, h) do { _Pragma("unroll") for (int m = 0; m < 4; ++m) _Pragma("unroll") for (int k = 0; k < 2; ++k) dst[m][k] = *(const LAS bf16x8*)(lds + PG8_SA(b, h) + aoff + m * 2048 + k * 1024); } while (0)
; #define PG8_LDB(dst, b, h) do { _Pragma("unroll") for (int n = 0; n < 2; ++n) _Pragma("unroll") for (int k = 0; k < 2; ++k) dst[n][k] = *(const LAS bf16x8*)(lds + PG8_SB(b, h) + boff + n * 2048 + k * 1024); } while (0)
; #define PG8_MMA(ai, bj, At, Bt) do { __builtin_amdgcn_s_setprio(1); _Pragma("unroll") for (int m = 0; m < 4; ++m) _Pragma("unroll") for (int n = 0; n < 2; ++n) _Pragma("unroll") for (int k = 0; k < 2; ++k) \
;         acc[ai][bj][m][n] = __builtin_amdgcn_mfma_f32_16x16x32_bf16(Bt[n][k], At[m][k], acc[ai][bj][m][n], 0, 0, 0); __builtin_amdgcn_s_setprio(0); } while (0)
; #define PG8_WAIT_V(n) asm volatile("s_waitcnt vmcnt(" #n ")" ::: "memory")
; #define PG8_WAIT_L(n) asm volatile("s_waitcnt lgkmcnt(" #n ")" ::: "memory")
; #define PG8_BAR __builtin_amdgcn_s_barrier()
; #define PG8_SCHED __builtin_amdgcn_sched_barrier(0)
; template <class Epi>
; __device__ __forceinline__ void gemm_phase(LAS unsigned char* lds, const Gemm g, const StaticOrder& S, const Epi& E, const int wid) {
;     ...
;             PG8_LDB(B0, 1, 0); PG8_LDB(B1, 1, 1); PG8_SCHED; PG8_LDA(At, 1, 0); PG8_STAGE(PG8_SA(0, 1), a2 + hstepA, voffA);
;             PG8_WAIT_V(8); PG8_WAIT_L(0); PG8_BAR; PG8_MMA(0, 0, At, B0); PG8_MMA(0, 1, At, B1); PG8_BAR; PG8_SCHED;
;             PG8_LDA(At, 1, 1); PG8_STAGE(PG8_SB(1, 0), b3, voffB); PG8_STAGE(PG8_SB(1, 1), b3 + hstepB, voffB); PG8_STAGE(PG8_SA(1, 0), a3, voffA);
;             PG8_WAIT_V(8); PG8_WAIT_L(0); PG8_BAR; PG8_MMA(1, 0, At, B0); PG8_MMA(1, 1, At, B1); PG8_BAR; PG8_SCHED;
;         }
	s_add_i32 s46, 0, 0x18000
	s_add_i32 s47, 0, 0x1c000
	v_add_u32_e32 v164, s46, v154
	v_add_u32_e32 v180, s47, v154
	ds_read_b128 v[144:147], v164
	ds_read_b128 v[148:151], v164 offset:1024
	ds_read_b128 v[160:163], v164 offset:2048
	ds_read_b128 v[164:167], v164 offset:3072
	ds_read_b128 v[168:171], v180
	ds_read_b128 v[172:175], v180 offset:1024
	ds_read_b128 v[176:179], v180 offset:2048
	ds_read_b128 v[180:183], v180 offset:3072
	s_add_u32 s24, s50, 0x80000
	s_addc_u32 s25, s51, 0
	s_mov_b32 m0, s26
	s_nop 0
	global_load_lds_dwordx4 v134, s[24:25]
	s_mov_b32 m0, s27
	s_nop 0
	global_load_lds_dwordx4 v130, s[24:25]
	ds_read_b128 v[184:187], v159 offset:32768
	ds_read_b128 v[188:191], v159 offset:33792
	ds_read_b128 v[192:195], v159 offset:34816
	ds_read_b128 v[196:199], v159 offset:35840
	ds_read_b128 v[200:203], v159 offset:36864
	ds_read_b128 v[204:207], v159 offset:37888
	ds_read_b128 v[208:211], v159 offset:38912
	ds_read_b128 v[212:215], v159 offset:39936
	s_waitcnt vmcnt(8)
	s_waitcnt lgkmcnt(0)
	s_barrier
	s_setprio 1
	v_mfma_f32_16x16x32_bf16 v[124:127], v[144:147], v[184:187], v[124:127]
	v_mfma_f32_16x16x32_bf16 v[120:123], v[160:163], v[184:187], v[120:123]
	v_mfma_f32_16x16x32_bf16 v[116:119], v[144:147], v[192:195], v[116:119]
	v_mfma_f32_16x16x32_bf16 v[112:115], v[160:163], v[192:195], v[112:115]
	v_mfma_f32_16x16x32_bf16 v[108:111], v[144:147], v[200:203], v[108:111]
	v_mfma_f32_16x16x32_bf16 v[104:107], v[160:163], v[200:203], v[104:107]
	v_mfma_f32_16x16x32_bf16 v[100:103], v[144:147], v[208:211], v[100:103]
	v_mfma_f32_16x16x32_bf16 v[96:99], v[160:163], v[208:211], v[96:99]
	v_mfma_f32_16x16x32_bf16 v[124:127], v[148:151], v[188:191], v[124:127]
	v_mfma_f32_16x16x32_bf16 v[120:123], v[164:167], v[188:191], v[120:123]
	v_mfma_f32_16x16x32_bf16 v[116:119], v[148:151], v[196:199], v[116:119]
	v_mfma_f32_16x16x32_bf16 v[112:115], v[164:167], v[196:199], v[112:115]
	v_mfma_f32_16x16x32_bf16 v[108:111], v[148:151], v[204:207], v[108:111]
	v_mfma_f32_16x16x32_bf16 v[104:107], v[164:167], v[204:207], v[104:107]
	v_mfma_f32_16x16x32_bf16 v[100:103], v[148:151], v[212:215], v[100:103]
	v_mfma_f32_16x16x32_bf16 v[96:99], v[164:167], v[212:215], v[96:99]
	v_mfma_f32_16x16x32_bf16 v[76:79], v[168:171], v[184:187], v[76:79]
	v_mfma_f32_16x16x32_bf16 v[64:67], v[176:179], v[184:187], v[64:67]
	v_mfma_f32_16x16x32_bf16 v[56:59], v[168:171], v[192:195], v[56:59]
	v_mfma_f32_16x16x32_bf16 v[48:51], v[176:179], v[192:195], v[48:51]
	v_mfma_f32_16x16x32_bf16 v[44:47], v[168:171], v[200:203], v[44:47]
	v_mfma_f32_16x16x32_bf16 v[40:43], v[176:179], v[200:203], v[40:43]
	v_mfma_f32_16x16x32_bf16 v[36:39], v[168:171], v[208:211], v[36:39]
	v_mfma_f32_16x16x32_bf16 v[32:35], v[176:179], v[208:211], v[32:35]
	v_mfma_f32_16x16x32_bf16 v[76:79], v[172:175], v[188:191], v[76:79]
	v_mfma_f32_16x16x32_bf16 v[64:67], v[180:183], v[188:191], v[64:67]
	v_mfma_f32_16x16x32_bf16 v[56:59], v[172:175], v[196:199], v[56:59]
	v_mfma_f32_16x16x32_bf16 v[48:51], v[180:183], v[196:199], v[48:51]
	v_mfma_f32_16x16x32_bf16 v[44:47], v[172:175], v[204:207], v[44:47]
	v_mfma_f32_16x16x32_bf16 v[40:43], v[180:183], v[204:207], v[40:43]
	v_mfma_f32_16x16x32_bf16 v[36:39], v[172:175], v[212:215], v[36:39]
	v_mfma_f32_16x16x32_bf16 v[32:35], v[180:183], v[212:215], v[32:35]
	s_setprio 0
	s_barrier
	s_add_i32 s24, s46, s94
	s_add_u32 s98, s48, 0x80
	s_addc_u32 s99, s49, 0
	s_mov_b32 m0, s24
	s_nop 0
	global_load_lds_dwordx4 v132, s[98:99]
	s_add_i32 m0, s24, 0x2000
	s_add_u32 s24, s48, 0x80080
	s_addc_u32 s25, s49, 0
	s_add_i32 s46, s47, s94
	global_load_lds_dwordx4 v128, s[98:99]
	s_mov_b32 m0, s46
	s_nop 0
	global_load_lds_dwordx4 v132, s[24:25]
	s_add_i32 m0, s46, 0x2000
	s_nop 0
	global_load_lds_dwordx4 v128, s[24:25]
	s_add_u32 s100, s50, 0x80
	s_addc_u32 s101, s51, 0
	s_mov_b32 m0, s29
	s_nop 0
	global_load_lds_dwordx4 v134, s[100:101]
	s_mov_b32 m0, s34
	s_nop 0
	global_load_lds_dwordx4 v130, s[100:101]
	ds_read_b128 v[184:187], v159 offset:49152
	ds_read_b128 v[188:191], v159 offset:50176
	ds_read_b128 v[192:195], v159 offset:51200
	ds_read_b128 v[196:199], v159 offset:52224
	ds_read_b128 v[200:203], v159 offset:53248
	ds_read_b128 v[204:207], v159 offset:54272
	ds_read_b128 v[208:211], v159 offset:55296
	ds_read_b128 v[212:215], v159 offset:56320
	s_waitcnt vmcnt(8)
	s_waitcnt lgkmcnt(0)
	s_barrier
	s_setprio 1
	v_mfma_f32_16x16x32_bf16 v[92:95], v[144:147], v[184:187], v[92:95]
	v_mfma_f32_16x16x32_bf16 v[88:91], v[160:163], v[184:187], v[88:91]
	v_mfma_f32_16x16x32_bf16 v[84:87], v[144:147], v[192:195], v[84:87]
	v_mfma_f32_16x16x32_bf16 v[80:83], v[160:163], v[192:195], v[80:83]
	v_mfma_f32_16x16x32_bf16 v[72:75], v[144:147], v[200:203], v[72:75]
	v_mfma_f32_16x16x32_bf16 v[68:71], v[160:163], v[200:203], v[68:71]
	v_mfma_f32_16x16x32_bf16 v[60:63], v[144:147], v[208:211], v[60:63]
	v_mfma_f32_16x16x32_bf16 v[52:55], v[160:163], v[208:211], v[52:55]
	v_mfma_f32_16x16x32_bf16 v[92:95], v[148:151], v[188:191], v[92:95]
	v_mfma_f32_16x16x32_bf16 v[88:91], v[164:167], v[188:191], v[88:91]
	v_mfma_f32_16x16x32_bf16 v[84:87], v[148:151], v[196:199], v[84:87]
	v_mfma_f32_16x16x32_bf16 v[80:83], v[164:167], v[196:199], v[80:83]
	v_mfma_f32_16x16x32_bf16 v[72:75], v[148:151], v[204:207], v[72:75]
	v_mfma_f32_16x16x32_bf16 v[68:71], v[164:167], v[204:207], v[68:71]
	v_mfma_f32_16x16x32_bf16 v[60:63], v[148:151], v[212:215], v[60:63]
	v_mfma_f32_16x16x32_bf16 v[52:55], v[164:167], v[212:215], v[52:55]
	v_mfma_f32_16x16x32_bf16 v[28:31], v[168:171], v[184:187], v[28:31]
	v_mfma_f32_16x16x32_bf16 v[24:27], v[176:179], v[184:187], v[24:27]
	v_mfma_f32_16x16x32_bf16 v[20:23], v[168:171], v[192:195], v[20:23]
	v_mfma_f32_16x16x32_bf16 v[16:19], v[176:179], v[192:195], v[16:19]
	v_mfma_f32_16x16x32_bf16 v[12:15], v[168:171], v[200:203], v[12:15]
	v_mfma_f32_16x16x32_bf16 v[8:11], v[176:179], v[200:203], v[8:11]
	v_mfma_f32_16x16x32_bf16 v[4:7], v[168:171], v[208:211], v[4:7]
	v_mfma_f32_16x16x32_bf16 v[0:3], v[176:179], v[208:211], v[0:3]
	v_mfma_f32_16x16x32_bf16 v[28:31], v[172:175], v[188:191], v[28:31]
	v_mfma_f32_16x16x32_bf16 v[24:27], v[180:183], v[188:191], v[24:27]
	v_mfma_f32_16x16x32_bf16 v[20:23], v[172:175], v[196:199], v[20:23]
	v_mfma_f32_16x16x32_bf16 v[16:19], v[180:183], v[196:199], v[16:19]
	v_mfma_f32_16x16x32_bf16 v[12:15], v[172:175], v[204:207], v[12:15]
	v_mfma_f32_16x16x32_bf16 v[8:11], v[180:183], v[204:207], v[8:11]
	v_mfma_f32_16x16x32_bf16 v[4:7], v[172:175], v[212:215], v[4:7]
	v_mfma_f32_16x16x32_bf16 v[0:3], v[180:183], v[212:215], v[0:3]
	s_setprio 0
	s_barrier
	s_add_i32 s54, s54, 2
	s_add_u32 s52, s52, 0x100
	s_addc_u32 s53, s53, 0
	s_cmp_gt_u32 s54, 29
	s_mov_b64 s[46:47], s[6:7]
	s_cbranch_scc0 .LBB0_1727
	s_and_b64 vcc, exec, s[22:23]
	s_cbranch_vccz .LBB0_1730
	s_barrier

; #define PG8_STAGE(bufoff, gbase, voff) do { _Pragma("unroll") for (int _i = 0; _i < 2; ++_i) \
;         __builtin_amdgcn_global_load_lds((const unsigned*)((const char*)(gbase) + (voff)[_i]), (LAS unsigned*)(lds + (bufoff) + ldsw + _i * 8192), 16, 0, 0); } while (0)
; #define PG8_LDA(dst, b, h) do { _Pragma("unroll") for (int m = 0; m < 4; ++m) _Pragma("unroll") for (int k = 0; k < 2; ++k) dst[m][k] = *(const LAS bf16x8*)(lds + PG8_SA(b, h) + aoff + m * 2048 + k * 1024); } while (0)
; #define PG8_LDB(dst, b, h) do { _Pragma("unroll") for (int n = 0; n < 2; ++n) _Pragma("unroll") for (int k = 0; k < 2; ++k) dst[n][k] = *(const LAS bf16x8*)(lds + PG8_SB(b, h) + boff + n * 2048 + k * 1024); } while (0)
; #define PG8_MMA(ai, bj, At, Bt) do { __builtin_amdgcn_s_setprio(1); _Pragma("unroll") for (int m = 0; m < 4; ++m) _Pragma("unroll") for (int n = 0; n < 2; ++n) _Pragma("unroll") for (int k = 0; k < 2; ++k) \
;         acc[ai][bj][m][n] = __builtin_amdgcn_mfma_f32_16x16x32_bf16(Bt[n][k], At[m][k], acc[ai][bj][m][n], 0, 0, 0); __builtin_amdgcn_s_setprio(0); } while (0)
; #define PG8_WAIT_V(n) asm volatile("s_waitcnt vmcnt(" #n ")" ::: "memory")
; #define PG8_WAIT_L(n) asm volatile("s_waitcnt lgkmcnt(" #n ")" ::: "memory")
; #define PG8_BAR __builtin_amdgcn_s_barrier()
; #define PG8_SCHED __builtin_amdgcn_sched_barrier(0)
; template <class Epi>
; __device__ __forceinline__ void gemm_phase(LAS unsigned char* lds, const Gemm g, const StaticOrder& S, const Epi& E, const int wid) {
;     ...
;         for (int t = 0; t < nt; t += 2) {
;             const bool last = (t == nt - 2);
;             const char* a1 = cA + (size_t)(t + 1) * kstep;
;             const char* a2 = last ? nA : cA + (size_t)(t + 2) * kstep; const char* b2 = last ? nB : cB + (size_t)(t + 2) * kstep;
;             const char* a3 = a2 + kstep; const char* b3 = b2 + kstep;
;             PG8_LDB(B0, 0, 0); PG8_LDB(B1, 0, 1); PG8_SCHED; PG8_LDA(At, 0, 0); PG8_STAGE(PG8_SA(1, 1), a1 + hstepA, voffA);
;             PG8_WAIT_V(8); PG8_WAIT_L(0); PG8_BAR; PG8_MMA(0, 0, At, B0); PG8_MMA(0, 1, At, B1); PG8_BAR; PG8_SCHED;
;             PG8_LDA(At, 0, 1); PG8_STAGE(PG8_SB(0, 0), b2, voffB); PG8_STAGE(PG8_SB(0, 1), b2 + hstepB, voffB); PG8_STAGE(PG8_SA(0, 0), a2, voffA);
;             PG8_WAIT_V(8); PG8_WAIT_L(0); PG8_BAR; PG8_MMA(1, 0, At, B0); PG8_MMA(1, 1, At, B1); PG8_BAR; PG8_SCHED;
.LBB0_1773:
	ds_read_b128 v[150:153], v147
	ds_read_b128 v[154:157], v147 offset:1024
	ds_read_b128 v[158:161], v147 offset:2048
	ds_read_b128 v[162:165], v147 offset:3072
	ds_read_b128 v[166:169], v148
	ds_read_b128 v[170:173], v148 offset:1024
	ds_read_b128 v[174:177], v148 offset:2048
	ds_read_b128 v[178:181], v148 offset:3072
	s_add_u32 s6, s42, 0x100
	s_addc_u32 s7, s43, 0
	s_cmp_eq_u32 s54, 28
	s_cselect_b32 s47, s21, s7
	s_cselect_b32 s46, s20, s6
	s_cselect_b32 s45, s19, s53
	s_cselect_b32 s44, s51, s52
	s_add_i32 m0, s15, 0xc000
	s_nop 0
	global_load_lds_dwordx4 v136, s[42:43]
	s_add_i32 m0, s15, 0xe000
	s_nop 0
	global_load_lds_dwordx4 v138, s[42:43]
	ds_read_b128 v[182:185], v149
	ds_read_b128 v[186:189], v149 offset:1024
	ds_read_b128 v[190:193], v149 offset:2048
	ds_read_b128 v[194:197], v149 offset:3072
	ds_read_b128 v[198:201], v149 offset:4096
	ds_read_b128 v[202:205], v149 offset:5120
	ds_read_b128 v[206:209], v149 offset:6144
	ds_read_b128 v[210:213], v149 offset:7168
	s_waitcnt vmcnt(8)
	s_waitcnt lgkmcnt(0)
	s_barrier
	s_setprio 1
	v_mfma_f32_16x16x32_bf16 v[124:127], v[150:153], v[182:185], v[124:127]
	v_mfma_f32_16x16x32_bf16 v[120:123], v[158:161], v[182:185], v[120:123]
	v_mfma_f32_16x16x32_bf16 v[108:111], v[150:153], v[190:193], v[108:111]
	v_mfma_f32_16x16x32_bf16 v[104:107], v[158:161], v[190:193], v[104:107]
	v_mfma_f32_16x16x32_bf16 v[92:95], v[150:153], v[198:201], v[92:95]
	v_mfma_f32_16x16x32_bf16 v[88:91], v[158:161], v[198:201], v[88:91]
	v_mfma_f32_16x16x32_bf16 v[76:79], v[150:153], v[206:209], v[76:79]
	v_mfma_f32_16x16x32_bf16 v[72:75], v[158:161], v[206:209], v[72:75]
	v_mfma_f32_16x16x32_bf16 v[124:127], v[154:157], v[186:189], v[124:127]
	v_mfma_f32_16x16x32_bf16 v[120:123], v[162:165], v[186:189], v[120:123]
	v_mfma_f32_16x16x32_bf16 v[108:111], v[154:157], v[194:197], v[108:111]
	v_mfma_f32_16x16x32_bf16 v[104:107], v[162:165], v[194:197], v[104:107]
	v_mfma_f32_16x16x32_bf16 v[92:95], v[154:157], v[202:205], v[92:95]
	v_mfma_f32_16x16x32_bf16 v[88:91], v[162:165], v[202:205], v[88:91]
	v_mfma_f32_16x16x32_bf16 v[76:79], v[154:157], v[210:213], v[76:79]
	v_mfma_f32_16x16x32_bf16 v[72:75], v[162:165], v[210:213], v[72:75]
	v_mfma_f32_16x16x32_bf16 v[116:119], v[166:169], v[182:185], v[116:119]
	v_mfma_f32_16x16x32_bf16 v[112:115], v[174:177], v[182:185], v[112:115]
	v_mfma_f32_16x16x32_bf16 v[100:103], v[166:169], v[190:193], v[100:103]
	v_mfma_f32_16x16x32_bf16 v[96:99], v[174:177], v[190:193], v[96:99]
	v_mfma_f32_16x16x32_bf16 v[84:87], v[166:169], v[198:201], v[84:87]
	v_mfma_f32_16x16x32_bf16 v[80:83], v[174:177], v[198:201], v[80:83]
	v_mfma_f32_16x16x32_bf16 v[68:71], v[166:169], v[206:209], v[68:71]
	v_mfma_f32_16x16x32_bf16 v[64:67], v[174:177], v[206:209], v[64:67]
	v_mfma_f32_16x16x32_bf16 v[116:119], v[170:173], v[186:189], v[116:119]
	v_mfma_f32_16x16x32_bf16 v[112:115], v[178:181], v[186:189], v[112:115]
	v_mfma_f32_16x16x32_bf16 v[100:103], v[170:173], v[194:197], v[100:103]
	v_mfma_f32_16x16x32_bf16 v[96:99], v[178:181], v[194:197], v[96:99]
	v_mfma_f32_16x16x32_bf16 v[84:87], v[170:173], v[202:205], v[84:87]
	v_mfma_f32_16x16x32_bf16 v[80:83], v[178:181], v[202:205], v[80:83]
	v_mfma_f32_16x16x32_bf16 v[68:71], v[170:173], v[210:213], v[68:71]
	v_mfma_f32_16x16x32_bf16 v[64:67], v[178:181], v[210:213], v[64:67]
	s_setprio 0
	s_barrier
	s_add_i32 s24, s36, s94
	s_mov_b32 m0, s24
	s_nop 0
	global_load_lds_dwordx4 v132, s[44:45]
	s_add_i32 m0, s24, 0x2000
	s_add_u32 s24, s44, 0x80000
	s_addc_u32 s25, s45, 0
	s_add_i32 s42, s37, s94
	global_load_lds_dwordx4 v128, s[44:45]
	s_mov_b32 m0, s42
	s_nop 0
	global_load_lds_dwordx4 v132, s[24:25]
	s_add_i32 m0, s42, 0x2000
	s_nop 0
	global_load_lds_dwordx4 v128, s[24:25]
	s_mov_b32 m0, s15
	s_nop 0
	global_load_lds_dwordx4 v134, s[46:47]
	s_mov_b32 m0, s26
	s_nop 0
	global_load_lds_dwordx4 v130, s[46:47]
	ds_read_b128 v[182:185], v149 offset:16384
	ds_read_b128 v[186:189], v149 offset:17408
	ds_read_b128 v[190:193], v149 offset:18432
	ds_read_b128 v[194:197], v149 offset:19456
	ds_read_b128 v[198:201], v149 offset:20480
	ds_read_b128 v[202:205], v149 offset:21504
	ds_read_b128 v[206:209], v149 offset:22528
	ds_read_b128 v[210:213], v149 offset:23552
	s_waitcnt vmcnt(8)
	s_waitcnt lgkmcnt(0)
	s_barrier
	s_setprio 1
	v_mfma_f32_16x16x32_bf16 v[60:63], v[150:153], v[182:185], v[60:63]
	v_mfma_f32_16x16x32_bf16 v[56:59], v[158:161], v[182:185], v[56:59]
	v_mfma_f32_16x16x32_bf16 v[44:47], v[150:153], v[190:193], v[44:47]
	v_mfma_f32_16x16x32_bf16 v[40:43], v[158:161], v[190:193], v[40:43]
	v_mfma_f32_16x16x32_bf16 v[28:31], v[150:153], v[198:201], v[28:31]
	v_mfma_f32_16x16x32_bf16 v[24:27], v[158:161], v[198:201], v[24:27]
	v_mfma_f32_16x16x32_bf16 v[12:15], v[150:153], v[206:209], v[12:15]
	v_mfma_f32_16x16x32_bf16 v[8:11], v[158:161], v[206:209], v[8:11]
	v_mfma_f32_16x16x32_bf16 v[60:63], v[154:157], v[186:189], v[60:63]
	v_mfma_f32_16x16x32_bf16 v[56:59], v[162:165], v[186:189], v[56:59]
	v_mfma_f32_16x16x32_bf16 v[44:47], v[154:157], v[194:197], v[44:47]
	v_mfma_f32_16x16x32_bf16 v[40:43], v[162:165], v[194:197], v[40:43]
	v_mfma_f32_16x16x32_bf16 v[28:31], v[154:157], v[202:205], v[28:31]
	v_mfma_f32_16x16x32_bf16 v[24:27], v[162:165], v[202:205], v[24:27]
	v_mfma_f32_16x16x32_bf16 v[12:15], v[154:157], v[210:213], v[12:15]
	v_mfma_f32_16x16x32_bf16 v[8:11], v[162:165], v[210:213], v[8:11]
	v_mfma_f32_16x16x32_bf16 v[52:55], v[166:169], v[182:185], v[52:55]
	v_mfma_f32_16x16x32_bf16 v[48:51], v[174:177], v[182:185], v[48:51]
	v_mfma_f32_16x16x32_bf16 v[36:39], v[166:169], v[190:193], v[36:39]
	v_mfma_f32_16x16x32_bf16 v[32:35], v[174:177], v[190:193], v[32:35]
	v_mfma_f32_16x16x32_bf16 v[20:23], v[166:169], v[198:201], v[20:23]
	v_mfma_f32_16x16x32_bf16 v[16:19], v[174:177], v[198:201], v[16:19]
	v_mfma_f32_16x16x32_bf16 v[4:7], v[166:169], v[206:209], v[4:7]
	v_mfma_f32_16x16x32_bf16 v[0:3], v[174:177], v[206:209], v[0:3]
	v_mfma_f32_16x16x32_bf16 v[52:55], v[170:173], v[186:189], v[52:55]
	v_mfma_f32_16x16x32_bf16 v[48:51], v[178:181], v[186:189], v[48:51]
	v_mfma_f32_16x16x32_bf16 v[36:39], v[170:173], v[194:197], v[36:39]
	v_mfma_f32_16x16x32_bf16 v[32:35], v[178:181], v[194:197], v[32:35]
	v_mfma_f32_16x16x32_bf16 v[20:23], v[170:173], v[202:205], v[20:23]
	v_mfma_f32_16x16x32_bf16 v[16:19], v[178:181], v[202:205], v[16:19]
	v_mfma_f32_16x16x32_bf16 v[4:7], v[170:173], v[210:213], v[4:7]
	v_mfma_f32_16x16x32_bf16 v[0:3], v[178:181], v[210:213], v[0:3]
	s_setprio 0
	s_barrier
; #define PG8_STAGE(bufoff, gbase, voff) do { _Pragma("unroll") for (int _i = 0; _i < 2; ++_i) \
;         __builtin_amdgcn_global_load_lds((const unsigned*)((const char*)(gbase) + (voff)[_i]), (LAS unsigned*)(lds + (bufoff) + ldsw + _i * 8192), 16, 0, 0); } while (0)
; #define PG8_LDA(dst, b, h) do { _Pragma("unroll") for (int m = 0; m < 4; ++m) _Pragma("unroll") for (int k = 0; k < 2; ++k) dst[m][k] = *(const LAS bf16x8*)(lds + PG8_SA(b, h) + aoff + m * 2048 + k * 1024); } while (0)
; #define PG8_LDB(dst, b, h) do { _Pragma("unroll") for (int n = 0; n < 2; ++n) _Pragma("unroll") for (int k = 0; k < 2; ++k) dst[n][k] = *(const LAS bf16x8*)(lds + PG8_SB(b, h) + boff + n * 2048 + k * 1024); } while (0)
; #define PG8_MMA(ai, bj, At, Bt) do { __builtin_amdgcn_s_setprio(1); _Pragma("unroll") for (int m = 0; m < 4; ++m) _Pragma("unroll") for (int n = 0; n < 2; ++n) _Pragma("unroll") for (int k = 0; k < 2; ++k) \
;         acc[ai][bj][m][n] = __builtin_amdgcn_mfma_f32_16x16x32_bf16(Bt[n][k], At[m][k], acc[ai][bj][m][n], 0, 0, 0); __builtin_amdgcn_s_setprio(0); } while (0)
; #define PG8_WAIT_V(n) asm volatile("s_waitcnt vmcnt(" #n ")" ::: "memory")
; #define PG8_WAIT_L(n) asm volatile("s_waitcnt lgkmcnt(" #n ")" ::: "memory")
; #define PG8_BAR __builtin_amdgcn_s_barrier()
; #define PG8_SCHED __builtin_amdgcn_sched_barrier(0)
; template <class Epi>
; __device__ __forceinline__ void gemm_phase(LAS unsigned char* lds, const Gemm g, const StaticOrder& S, const Epi& E, const int wid) {
;     ...
;             PG8_LDB(B0, 1, 0); PG8_LDB(B1, 1, 1); PG8_SCHED; PG8_LDA(At, 1, 0); PG8_STAGE(PG8_SA(0, 1), a2 + hstepA, voffA);
;             PG8_WAIT_V(8); PG8_WAIT_L(0); PG8_BAR; PG8_MMA(0, 0, At, B0); PG8_MMA(0, 1, At, B1); PG8_BAR; PG8_SCHED;
;             PG8_LDA(At, 1, 1); PG8_STAGE(PG8_SB(1, 0), b3, voffB); PG8_STAGE(PG8_SB(1, 1), b3 + hstepB, voffB); PG8_STAGE(PG8_SA(1, 0), a3, voffA);
;             PG8_WAIT_V(8); PG8_WAIT_L(0); PG8_BAR; PG8_MMA(1, 0, At, B0); PG8_MMA(1, 1, At, B1); PG8_BAR; PG8_SCHED;
;         }
	s_add_i32 s42, 0, 0x18000
	s_add_i32 s43, 0, 0x1c000
	v_add_u32_e32 v162, s42, v144
	v_add_u32_e32 v178, s43, v144
	ds_read_b128 v[150:153], v162
	ds_read_b128 v[154:157], v162 offset:1024
	ds_read_b128 v[158:161], v162 offset:2048
	ds_read_b128 v[162:165], v162 offset:3072
	ds_read_b128 v[166:169], v178
	ds_read_b128 v[170:173], v178 offset:1024
	ds_read_b128 v[174:177], v178 offset:2048
	ds_read_b128 v[178:181], v178 offset:3072
	s_add_u32 s24, s46, 0x80000
	s_addc_u32 s25, s47, 0
	s_mov_b32 m0, s27
	s_nop 0
	global_load_lds_dwordx4 v134, s[24:25]
	s_mov_b32 m0, s28
	s_nop 0
	global_load_lds_dwordx4 v130, s[24:25]
	ds_read_b128 v[182:185], v149 offset:32768
	ds_read_b128 v[186:189], v149 offset:33792
	ds_read_b128 v[190:193], v149 offset:34816
	ds_read_b128 v[194:197], v149 offset:35840
	ds_read_b128 v[198:201], v149 offset:36864
	ds_read_b128 v[202:205], v149 offset:37888
	ds_read_b128 v[206:209], v149 offset:38912
	ds_read_b128 v[210:213], v149 offset:39936
	s_waitcnt vmcnt(8)
	s_waitcnt lgkmcnt(0)
	s_barrier
	s_setprio 1
	v_mfma_f32_16x16x32_bf16 v[124:127], v[150:153], v[182:185], v[124:127]
	v_mfma_f32_16x16x32_bf16 v[120:123], v[158:161], v[182:185], v[120:123]
	v_mfma_f32_16x16x32_bf16 v[108:111], v[150:153], v[190:193], v[108:111]
	v_mfma_f32_16x16x32_bf16 v[104:107], v[158:161], v[190:193], v[104:107]
	v_mfma_f32_16x16x32_bf16 v[92:95], v[150:153], v[198:201], v[92:95]
	v_mfma_f32_16x16x32_bf16 v[88:91], v[158:161], v[198:201], v[88:91]
	v_mfma_f32_16x16x32_bf16 v[76:79], v[150:153], v[206:209], v[76:79]
	v_mfma_f32_16x16x32_bf16 v[72:75], v[158:161], v[206:209], v[72:75]
	v_mfma_f32_16x16x32_bf16 v[124:127], v[154:157], v[186:189], v[124:127]
	v_mfma_f32_16x16x32_bf16 v[120:123], v[162:165], v[186:189], v[120:123]
	v_mfma_f32_16x16x32_bf16 v[108:111], v[154:157], v[194:197], v[108:111]
	v_mfma_f32_16x16x32_bf16 v[104:107], v[162:165], v[194:197], v[104:107]
	v_mfma_f32_16x16x32_bf16 v[92:95], v[154:157], v[202:205], v[92:95]
	v_mfma_f32_16x16x32_bf16 v[88:91], v[162:165], v[202:205], v[88:91]
	v_mfma_f32_16x16x32_bf16 v[76:79], v[154:157], v[210:213], v[76:79]
	v_mfma_f32_16x16x32_bf16 v[72:75], v[162:165], v[210:213], v[72:75]
	v_mfma_f32_16x16x32_bf16 v[116:119], v[166:169], v[182:185], v[116:119]
	v_mfma_f32_16x16x32_bf16 v[112:115], v[174:177], v[182:185], v[112:115]
	v_mfma_f32_16x16x32_bf16 v[100:103], v[166:169], v[190:193], v[100:103]
	v_mfma_f32_16x16x32_bf16 v[96:99], v[174:177], v[190:193], v[96:99]
	v_mfma_f32_16x16x32_bf16 v[84:87], v[166:169], v[198:201], v[84:87]
	v_mfma_f32_16x16x32_bf16 v[80:83], v[174:177], v[198:201], v[80:83]
	v_mfma_f32_16x16x32_bf16 v[68:71], v[166:169], v[206:209], v[68:71]
	v_mfma_f32_16x16x32_bf16 v[64:67], v[174:177], v[206:209], v[64:67]
	v_mfma_f32_16x16x32_bf16 v[116:119], v[170:173], v[186:189], v[116:119]
	v_mfma_f32_16x16x32_bf16 v[112:115], v[178:181], v[186:189], v[112:115]
	v_mfma_f32_16x16x32_bf16 v[100:103], v[170:173], v[194:197], v[100:103]
	v_mfma_f32_16x16x32_bf16 v[96:99], v[178:181], v[194:197], v[96:99]
	v_mfma_f32_16x16x32_bf16 v[84:87], v[170:173], v[202:205], v[84:87]
	v_mfma_f32_16x16x32_bf16 v[80:83], v[178:181], v[202:205], v[80:83]
	v_mfma_f32_16x16x32_bf16 v[68:71], v[170:173], v[210:213], v[68:71]
	v_mfma_f32_16x16x32_bf16 v[64:67], v[178:181], v[210:213], v[64:67]
	s_setprio 0
	s_barrier
	s_add_i32 s24, s42, s94
	s_add_u32 s98, s44, 0x80
	s_addc_u32 s99, s45, 0
	s_mov_b32 m0, s24
	s_nop 0
	global_load_lds_dwordx4 v132, s[98:99]
	s_add_i32 m0, s24, 0x2000
	s_add_u32 s24, s44, 0x80080
	s_addc_u32 s25, s45, 0
	s_add_i32 s42, s43, s94
	global_load_lds_dwordx4 v128, s[98:99]
	s_mov_b32 m0, s42
	s_nop 0
	global_load_lds_dwordx4 v132, s[24:25]
	s_add_i32 m0, s42, 0x2000
	s_nop 0
	global_load_lds_dwordx4 v128, s[24:25]
	s_add_u32 s100, s46, 0x80
	s_addc_u32 s101, s47, 0
	s_mov_b32 m0, s34
	s_nop 0
	global_load_lds_dwordx4 v134, s[100:101]
	s_mov_b32 m0, s35
	s_nop 0
	global_load_lds_dwordx4 v130, s[100:101]
	ds_read_b128 v[182:185], v149 offset:49152
	ds_read_b128 v[186:189], v149 offset:50176
	ds_read_b128 v[190:193], v149 offset:51200
	ds_read_b128 v[194:197], v149 offset:52224
	ds_read_b128 v[198:201], v149 offset:53248
	ds_read_b128 v[202:205], v149 offset:54272
	ds_read_b128 v[206:209], v149 offset:55296
	ds_read_b128 v[210:213], v149 offset:56320
	s_waitcnt vmcnt(8)
	s_waitcnt lgkmcnt(0)
	s_barrier
	s_setprio 1
	v_mfma_f32_16x16x32_bf16 v[60:63], v[150:153], v[182:185], v[60:63]
	v_mfma_f32_16x16x32_bf16 v[56:59], v[158:161], v[182:185], v[56:59]
	v_mfma_f32_16x16x32_bf16 v[44:47], v[150:153], v[190:193], v[44:47]
	v_mfma_f32_16x16x32_bf16 v[40:43], v[158:161], v[190:193], v[40:43]
	v_mfma_f32_16x16x32_bf16 v[28:31], v[150:153], v[198:201], v[28:31]
	v_mfma_f32_16x16x32_bf16 v[24:27], v[158:161], v[198:201], v[24:27]
	v_mfma_f32_16x16x32_bf16 v[12:15], v[150:153], v[206:209], v[12:15]
	v_mfma_f32_16x16x32_bf16 v[8:11], v[158:161], v[206:209], v[8:11]
	v_mfma_f32_16x16x32_bf16 v[60:63], v[154:157], v[186:189], v[60:63]
	v_mfma_f32_16x16x32_bf16 v[56:59], v[162:165], v[186:189], v[56:59]
	v_mfma_f32_16x16x32_bf16 v[44:47], v[154:157], v[194:197], v[44:47]
	v_mfma_f32_16x16x32_bf16 v[40:43], v[162:165], v[194:197], v[40:43]
	v_mfma_f32_16x16x32_bf16 v[28:31], v[154:157], v[202:205], v[28:31]
	v_mfma_f32_16x16x32_bf16 v[24:27], v[162:165], v[202:205], v[24:27]
	v_mfma_f32_16x16x32_bf16 v[12:15], v[154:157], v[210:213], v[12:15]
	v_mfma_f32_16x16x32_bf16 v[8:11], v[162:165], v[210:213], v[8:11]
	v_mfma_f32_16x16x32_bf16 v[52:55], v[166:169], v[182:185], v[52:55]
	v_mfma_f32_16x16x32_bf16 v[48:51], v[174:177], v[182:185], v[48:51]
	v_mfma_f32_16x16x32_bf16 v[36:39], v[166:169], v[190:193], v[36:39]
	v_mfma_f32_16x16x32_bf16 v[32:35], v[174:177], v[190:193], v[32:35]
	v_mfma_f32_16x16x32_bf16 v[20:23], v[166:169], v[198:201], v[20:23]
	v_mfma_f32_16x16x32_bf16 v[16:19], v[174:177], v[198:201], v[16:19]
	v_mfma_f32_16x16x32_bf16 v[4:7], v[166:169], v[206:209], v[4:7]
	v_mfma_f32_16x16x32_bf16 v[0:3], v[174:177], v[206:209], v[0:3]
	v_mfma_f32_16x16x32_bf16 v[52:55], v[170:173], v[186:189], v[52:55]
	v_mfma_f32_16x16x32_bf16 v[48:51], v[178:181], v[186:189], v[48:51]
	v_mfma_f32_16x16x32_bf16 v[36:39], v[170:173], v[194:197], v[36:39]
	v_mfma_f32_16x16x32_bf16 v[32:35], v[178:181], v[194:197], v[32:35]
	v_mfma_f32_16x16x32_bf16 v[20:23], v[170:173], v[202:205], v[20:23]
	v_mfma_f32_16x16x32_bf16 v[16:19], v[178:181], v[202:205], v[16:19]
	v_mfma_f32_16x16x32_bf16 v[4:7], v[170:173], v[210:213], v[4:7]
	v_mfma_f32_16x16x32_bf16 v[0:3], v[178:181], v[210:213], v[0:3]
	s_setprio 0
	s_barrier
	s_add_i32 s54, s54, 2
	s_add_u32 s52, s52, 0x100
	s_addc_u32 s53, s53, 0
	s_cmp_gt_u32 s54, 29
	s_mov_b64 s[42:43], s[6:7]
	s_cbranch_scc0 .LBB0_1773
	s_and_b64 vcc, exec, s[22:23]
	s_cbranch_vccz .LBB0_1776
	s_barrier

; #define PG8_STAGE(bufoff, gbase, voff) do { _Pragma("unroll") for (int _i = 0; _i < 2; ++_i) \
;         __builtin_amdgcn_global_load_lds((const unsigned*)((const char*)(gbase) + (voff)[_i]), (LAS unsigned*)(lds + (bufoff) + ldsw + _i * 8192), 16, 0, 0); } while (0)
; #define PG8_LDA(dst, b, h) do { _Pragma("unroll") for (int m = 0; m < 4; ++m) _Pragma("unroll") for (int k = 0; k < 2; ++k) dst[m][k] = *(const LAS bf16x8*)(lds + PG8_SA(b, h) + aoff + m * 2048 + k * 1024); } while (0)
; #define PG8_LDB(dst, b, h) do { _Pragma("unroll") for (int n = 0; n < 2; ++n) _Pragma("unroll") for (int k = 0; k < 2; ++k) dst[n][k] = *(const LAS bf16x8*)(lds + PG8_SB(b, h) + boff + n * 2048 + k * 1024); } while (0)
; #define PG8_MMA(ai, bj, At, Bt) do { __builtin_amdgcn_s_setprio(1); _Pragma("unroll") for (int m = 0; m < 4; ++m) _Pragma("unroll") for (int n = 0; n < 2; ++n) _Pragma("unroll") for (int k = 0; k < 2; ++k) \
;         acc[ai][bj][m][n] = __builtin_amdgcn_mfma_f32_16x16x32_bf16(Bt[n][k], At[m][k], acc[ai][bj][m][n], 0, 0, 0); __builtin_amdgcn_s_setprio(0); } while (0)
; #define PG8_WAIT_V(n) asm volatile("s_waitcnt vmcnt(" #n ")" ::: "memory")
; #define PG8_WAIT_L(n) asm volatile("s_waitcnt lgkmcnt(" #n ")" ::: "memory")
; #define PG8_BAR __builtin_amdgcn_s_barrier()
; #define PG8_SCHED __builtin_amdgcn_sched_barrier(0)
; template <class Epi>
; __device__ __forceinline__ void gemm_phase(LAS unsigned char* lds, const Gemm g, const StaticOrder& S, const Epi& E, const int wid) {
;     ...
;         for (int t = 0; t < nt; t += 2) {
;             const bool last = (t == nt - 2);
;             const char* a1 = cA + (size_t)(t + 1) * kstep;
;             const char* a2 = last ? nA : cA + (size_t)(t + 2) * kstep; const char* b2 = last ? nB : cB + (size_t)(t + 2) * kstep;
;             const char* a3 = a2 + kstep; const char* b3 = b2 + kstep;
;             PG8_LDB(B0, 0, 0); PG8_LDB(B1, 0, 1); PG8_SCHED; PG8_LDA(At, 0, 0); PG8_STAGE(PG8_SA(1, 1), a1 + hstepA, voffA);
;             PG8_WAIT_V(8); PG8_WAIT_L(0); PG8_BAR; PG8_MMA(0, 0, At, B0); PG8_MMA(0, 1, At, B1); PG8_BAR; PG8_SCHED;
;             PG8_LDA(At, 0, 1); PG8_STAGE(PG8_SB(0, 0), b2, voffB); PG8_STAGE(PG8_SB(0, 1), b2 + hstepB, voffB); PG8_STAGE(PG8_SA(0, 0), a2, voffA);
;             PG8_WAIT_V(8); PG8_WAIT_L(0); PG8_BAR; PG8_MMA(1, 0, At, B0); PG8_MMA(1, 1, At, B1); PG8_BAR; PG8_SCHED;
.LBB0_1810:
	ds_read_b128 v[144:147], v153
	ds_read_b128 v[156:159], v153 offset:1024
	ds_read_b128 v[160:163], v153 offset:2048
	ds_read_b128 v[164:167], v153 offset:3072
	ds_read_b128 v[168:171], v154
	ds_read_b128 v[172:175], v154 offset:1024
	ds_read_b128 v[176:179], v154 offset:2048
	ds_read_b128 v[180:183], v154 offset:3072
	s_add_u32 s26, s20, 0x100
	s_addc_u32 s27, s21, 0
	s_cmpk_eq_i32 s45, 0x54
	s_cselect_b32 s31, s7, s27
	s_cselect_b32 s30, s6, s26
	s_cselect_b32 s29, s19, s44
	s_cselect_b32 s28, s18, s43
	s_add_i32 m0, s1, 0xc000
	s_nop 0
	global_load_lds_dwordx4 v136, s[20:21]
	s_add_i32 m0, s1, 0xe000
	s_nop 0
	global_load_lds_dwordx4 v138, s[20:21]
	ds_read_b128 v[184:187], v155
	ds_read_b128 v[188:191], v155 offset:1024
	ds_read_b128 v[192:195], v155 offset:2048
	ds_read_b128 v[196:199], v155 offset:3072
	ds_read_b128 v[200:203], v155 offset:4096
	ds_read_b128 v[204:207], v155 offset:5120
	ds_read_b128 v[208:211], v155 offset:6144
	ds_read_b128 v[212:215], v155 offset:7168
	s_waitcnt vmcnt(8)
	s_waitcnt lgkmcnt(0)
	s_barrier
	s_setprio 1
	v_mfma_f32_16x16x32_bf16 v[124:127], v[144:147], v[184:187], v[124:127]
	v_mfma_f32_16x16x32_bf16 v[120:123], v[160:163], v[184:187], v[120:123]
	v_mfma_f32_16x16x32_bf16 v[116:119], v[144:147], v[192:195], v[116:119]
	v_mfma_f32_16x16x32_bf16 v[112:115], v[160:163], v[192:195], v[112:115]
	v_mfma_f32_16x16x32_bf16 v[108:111], v[144:147], v[200:203], v[108:111]
	v_mfma_f32_16x16x32_bf16 v[104:107], v[160:163], v[200:203], v[104:107]
	v_mfma_f32_16x16x32_bf16 v[100:103], v[144:147], v[208:211], v[100:103]
	v_mfma_f32_16x16x32_bf16 v[96:99], v[160:163], v[208:211], v[96:99]
	v_mfma_f32_16x16x32_bf16 v[124:127], v[156:159], v[188:191], v[124:127]
	v_mfma_f32_16x16x32_bf16 v[120:123], v[164:167], v[188:191], v[120:123]
	v_mfma_f32_16x16x32_bf16 v[116:119], v[156:159], v[196:199], v[116:119]
	v_mfma_f32_16x16x32_bf16 v[112:115], v[164:167], v[196:199], v[112:115]
	v_mfma_f32_16x16x32_bf16 v[108:111], v[156:159], v[204:207], v[108:111]
	v_mfma_f32_16x16x32_bf16 v[104:107], v[164:167], v[204:207], v[104:107]
	v_mfma_f32_16x16x32_bf16 v[100:103], v[156:159], v[212:215], v[100:103]
	v_mfma_f32_16x16x32_bf16 v[96:99], v[164:167], v[212:215], v[96:99]
	v_mfma_f32_16x16x32_bf16 v[68:71], v[168:171], v[184:187], v[68:71]
	v_mfma_f32_16x16x32_bf16 v[64:67], v[176:179], v[184:187], v[64:67]
	v_mfma_f32_16x16x32_bf16 v[52:55], v[168:171], v[192:195], v[52:55]
	v_mfma_f32_16x16x32_bf16 v[48:51], v[176:179], v[192:195], v[48:51]
	v_mfma_f32_16x16x32_bf16 v[44:47], v[168:171], v[200:203], v[44:47]
	v_mfma_f32_16x16x32_bf16 v[40:43], v[176:179], v[200:203], v[40:43]
	v_mfma_f32_16x16x32_bf16 v[36:39], v[168:171], v[208:211], v[36:39]
	v_mfma_f32_16x16x32_bf16 v[32:35], v[176:179], v[208:211], v[32:35]
	v_mfma_f32_16x16x32_bf16 v[68:71], v[172:175], v[188:191], v[68:71]
	v_mfma_f32_16x16x32_bf16 v[64:67], v[180:183], v[188:191], v[64:67]
	v_mfma_f32_16x16x32_bf16 v[52:55], v[172:175], v[196:199], v[52:55]
	v_mfma_f32_16x16x32_bf16 v[48:51], v[180:183], v[196:199], v[48:51]
	v_mfma_f32_16x16x32_bf16 v[44:47], v[172:175], v[204:207], v[44:47]
	v_mfma_f32_16x16x32_bf16 v[40:43], v[180:183], v[204:207], v[40:43]
	v_mfma_f32_16x16x32_bf16 v[36:39], v[172:175], v[212:215], v[36:39]
	v_mfma_f32_16x16x32_bf16 v[32:35], v[180:183], v[212:215], v[32:35]
	s_setprio 0
	s_barrier
	s_add_i32 s20, s0, s94
	s_mov_b32 m0, s20
	s_nop 0
	global_load_lds_dwordx4 v132, s[28:29]
	s_add_i32 m0, s20, 0x2000
	s_add_u32 s20, s28, 0x160000
	s_addc_u32 s21, s29, 0
	s_add_i32 s24, s38, s94
	global_load_lds_dwordx4 v128, s[28:29]
	s_mov_b32 m0, s24
	s_nop 0
	global_load_lds_dwordx4 v132, s[20:21]
	s_add_i32 m0, s24, 0x2000
	s_nop 0
	global_load_lds_dwordx4 v128, s[20:21]
	s_mov_b32 m0, s1
	s_nop 0
	global_load_lds_dwordx4 v134, s[30:31]
	s_mov_b32 m0, s12
	s_nop 0
	global_load_lds_dwordx4 v130, s[30:31]
	ds_read_b128 v[184:187], v155 offset:16384
	ds_read_b128 v[188:191], v155 offset:17408
	ds_read_b128 v[192:195], v155 offset:18432
	ds_read_b128 v[196:199], v155 offset:19456
	ds_read_b128 v[200:203], v155 offset:20480
	ds_read_b128 v[204:207], v155 offset:21504
	ds_read_b128 v[208:211], v155 offset:22528
	ds_read_b128 v[212:215], v155 offset:23552
	s_waitcnt vmcnt(8)
	s_waitcnt lgkmcnt(0)
	s_barrier
	s_setprio 1
	v_mfma_f32_16x16x32_bf16 v[92:95], v[144:147], v[184:187], v[92:95]
	v_mfma_f32_16x16x32_bf16 v[88:91], v[160:163], v[184:187], v[88:91]
	v_mfma_f32_16x16x32_bf16 v[84:87], v[144:147], v[192:195], v[84:87]
	v_mfma_f32_16x16x32_bf16 v[80:83], v[160:163], v[192:195], v[80:83]
	v_mfma_f32_16x16x32_bf16 v[76:79], v[144:147], v[200:203], v[76:79]
	v_mfma_f32_16x16x32_bf16 v[72:75], v[160:163], v[200:203], v[72:75]
	v_mfma_f32_16x16x32_bf16 v[60:63], v[144:147], v[208:211], v[60:63]
	v_mfma_f32_16x16x32_bf16 v[56:59], v[160:163], v[208:211], v[56:59]
	v_mfma_f32_16x16x32_bf16 v[92:95], v[156:159], v[188:191], v[92:95]
	v_mfma_f32_16x16x32_bf16 v[88:91], v[164:167], v[188:191], v[88:91]
	v_mfma_f32_16x16x32_bf16 v[84:87], v[156:159], v[196:199], v[84:87]
	v_mfma_f32_16x16x32_bf16 v[80:83], v[164:167], v[196:199], v[80:83]
	v_mfma_f32_16x16x32_bf16 v[76:79], v[156:159], v[204:207], v[76:79]
	v_mfma_f32_16x16x32_bf16 v[72:75], v[164:167], v[204:207], v[72:75]
	v_mfma_f32_16x16x32_bf16 v[60:63], v[156:159], v[212:215], v[60:63]
	v_mfma_f32_16x16x32_bf16 v[56:59], v[164:167], v[212:215], v[56:59]
	v_mfma_f32_16x16x32_bf16 v[28:31], v[168:171], v[184:187], v[28:31]
	v_mfma_f32_16x16x32_bf16 v[24:27], v[176:179], v[184:187], v[24:27]
	v_mfma_f32_16x16x32_bf16 v[20:23], v[168:171], v[192:195], v[20:23]
	v_mfma_f32_16x16x32_bf16 v[16:19], v[176:179], v[192:195], v[16:19]
	v_mfma_f32_16x16x32_bf16 v[12:15], v[168:171], v[200:203], v[12:15]
	v_mfma_f32_16x16x32_bf16 v[8:11], v[176:179], v[200:203], v[8:11]
	v_mfma_f32_16x16x32_bf16 v[4:7], v[168:171], v[208:211], v[4:7]
	v_mfma_f32_16x16x32_bf16 v[0:3], v[176:179], v[208:211], v[0:3]
	v_mfma_f32_16x16x32_bf16 v[28:31], v[172:175], v[188:191], v[28:31]
	v_mfma_f32_16x16x32_bf16 v[24:27], v[180:183], v[188:191], v[24:27]
	v_mfma_f32_16x16x32_bf16 v[20:23], v[172:175], v[196:199], v[20:23]
	v_mfma_f32_16x16x32_bf16 v[16:19], v[180:183], v[196:199], v[16:19]
	v_mfma_f32_16x16x32_bf16 v[12:15], v[172:175], v[204:207], v[12:15]
	v_mfma_f32_16x16x32_bf16 v[8:11], v[180:183], v[204:207], v[8:11]
	v_mfma_f32_16x16x32_bf16 v[4:7], v[172:175], v[212:215], v[4:7]
	v_mfma_f32_16x16x32_bf16 v[0:3], v[180:183], v[212:215], v[0:3]
	s_setprio 0
	s_barrier
; #define PG8_STAGE(bufoff, gbase, voff) do { _Pragma("unroll") for (int _i = 0; _i < 2; ++_i) \
;         __builtin_amdgcn_global_load_lds((const unsigned*)((const char*)(gbase) + (voff)[_i]), (LAS unsigned*)(lds + (bufoff) + ldsw + _i * 8192), 16, 0, 0); } while (0)
; #define PG8_LDA(dst, b, h) do { _Pragma("unroll") for (int m = 0; m < 4; ++m) _Pragma("unroll") for (int k = 0; k < 2; ++k) dst[m][k] = *(const LAS bf16x8*)(lds + PG8_SA(b, h) + aoff + m * 2048 + k * 1024); } while (0)
; #define PG8_LDB(dst, b, h) do { _Pragma("unroll") for (int n = 0; n < 2; ++n) _Pragma("unroll") for (int k = 0; k < 2; ++k) dst[n][k] = *(const LAS bf16x8*)(lds + PG8_SB(b, h) + boff + n * 2048 + k * 1024); } while (0)
; #define PG8_MMA(ai, bj, At, Bt) do { __builtin_amdgcn_s_setprio(1); _Pragma("unroll") for (int m = 0; m < 4; ++m) _Pragma("unroll") for (int n = 0; n < 2; ++n) _Pragma("unroll") for (int k = 0; k < 2; ++k) \
;         acc[ai][bj][m][n] = __builtin_amdgcn_mfma_f32_16x16x32_bf16(Bt[n][k], At[m][k], acc[ai][bj][m][n], 0, 0, 0); __builtin_amdgcn_s_setprio(0); } while (0)
; #define PG8_WAIT_V(n) asm volatile("s_waitcnt vmcnt(" #n ")" ::: "memory")
; #define PG8_WAIT_L(n) asm volatile("s_waitcnt lgkmcnt(" #n ")" ::: "memory")
; #define PG8_BAR __builtin_amdgcn_s_barrier()
; #define PG8_SCHED __builtin_amdgcn_sched_barrier(0)
; template <class Epi>
; __device__ __forceinline__ void gemm_phase(LAS unsigned char* lds, const Gemm g, const StaticOrder& S, const Epi& E, const int wid) {
;     ...
;             PG8_LDB(B0, 1, 0); PG8_LDB(B1, 1, 1); PG8_SCHED; PG8_LDA(At, 1, 0); PG8_STAGE(PG8_SA(0, 1), a2 + hstepA, voffA);
;             PG8_WAIT_V(8); PG8_WAIT_L(0); PG8_BAR; PG8_MMA(0, 0, At, B0); PG8_MMA(0, 1, At, B1); PG8_BAR; PG8_SCHED;
;             PG8_LDA(At, 1, 1); PG8_STAGE(PG8_SB(1, 0), b3, voffB); PG8_STAGE(PG8_SB(1, 1), b3 + hstepB, voffB); PG8_STAGE(PG8_SA(1, 0), a3, voffA);
;             PG8_WAIT_V(8); PG8_WAIT_L(0); PG8_BAR; PG8_MMA(1, 0, At, B0); PG8_MMA(1, 1, At, B1); PG8_BAR; PG8_SCHED;
;         }
	s_add_i32 s24, 0, 0x18000
	s_add_i32 s25, 0, 0x1c000
	v_add_u32_e32 v164, s24, v150
	v_add_u32_e32 v180, s25, v150
	ds_read_b128 v[144:147], v164
	ds_read_b128 v[156:159], v164 offset:1024
	ds_read_b128 v[160:163], v164 offset:2048
	ds_read_b128 v[164:167], v164 offset:3072
	ds_read_b128 v[168:171], v180
	ds_read_b128 v[172:175], v180 offset:1024
	ds_read_b128 v[176:179], v180 offset:2048
	ds_read_b128 v[180:183], v180 offset:3072
	s_add_u32 s20, s30, 0x160000
	s_addc_u32 s21, s31, 0
	s_mov_b32 m0, s15
	s_nop 0
	global_load_lds_dwordx4 v134, s[20:21]
	s_mov_b32 m0, s34
	s_nop 0
	global_load_lds_dwordx4 v130, s[20:21]
	ds_read_b128 v[184:187], v155 offset:32768
	ds_read_b128 v[188:191], v155 offset:33792
	ds_read_b128 v[192:195], v155 offset:34816
	ds_read_b128 v[196:199], v155 offset:35840
	ds_read_b128 v[200:203], v155 offset:36864
	ds_read_b128 v[204:207], v155 offset:37888
	ds_read_b128 v[208:211], v155 offset:38912
	ds_read_b128 v[212:215], v155 offset:39936
	s_waitcnt vmcnt(8)
	s_waitcnt lgkmcnt(0)
	s_barrier
	s_setprio 1
	v_mfma_f32_16x16x32_bf16 v[124:127], v[144:147], v[184:187], v[124:127]
	v_mfma_f32_16x16x32_bf16 v[120:123], v[160:163], v[184:187], v[120:123]
	v_mfma_f32_16x16x32_bf16 v[116:119], v[144:147], v[192:195], v[116:119]
	v_mfma_f32_16x16x32_bf16 v[112:115], v[160:163], v[192:195], v[112:115]
	v_mfma_f32_16x16x32_bf16 v[108:111], v[144:147], v[200:203], v[108:111]
	v_mfma_f32_16x16x32_bf16 v[104:107], v[160:163], v[200:203], v[104:107]
	v_mfma_f32_16x16x32_bf16 v[100:103], v[144:147], v[208:211], v[100:103]
	v_mfma_f32_16x16x32_bf16 v[96:99], v[160:163], v[208:211], v[96:99]
	v_mfma_f32_16x16x32_bf16 v[124:127], v[156:159], v[188:191], v[124:127]
	v_mfma_f32_16x16x32_bf16 v[120:123], v[164:167], v[188:191], v[120:123]
	v_mfma_f32_16x16x32_bf16 v[116:119], v[156:159], v[196:199], v[116:119]
	v_mfma_f32_16x16x32_bf16 v[112:115], v[164:167], v[196:199], v[112:115]
	v_mfma_f32_16x16x32_bf16 v[108:111], v[156:159], v[204:207], v[108:111]
	v_mfma_f32_16x16x32_bf16 v[104:107], v[164:167], v[204:207], v[104:107]
	v_mfma_f32_16x16x32_bf16 v[100:103], v[156:159], v[212:215], v[100:103]
	v_mfma_f32_16x16x32_bf16 v[96:99], v[164:167], v[212:215], v[96:99]
	v_mfma_f32_16x16x32_bf16 v[68:71], v[168:171], v[184:187], v[68:71]
	v_mfma_f32_16x16x32_bf16 v[64:67], v[176:179], v[184:187], v[64:67]
	v_mfma_f32_16x16x32_bf16 v[52:55], v[168:171], v[192:195], v[52:55]
	v_mfma_f32_16x16x32_bf16 v[48:51], v[176:179], v[192:195], v[48:51]
	v_mfma_f32_16x16x32_bf16 v[44:47], v[168:171], v[200:203], v[44:47]
	v_mfma_f32_16x16x32_bf16 v[40:43], v[176:179], v[200:203], v[40:43]
	v_mfma_f32_16x16x32_bf16 v[36:39], v[168:171], v[208:211], v[36:39]
	v_mfma_f32_16x16x32_bf16 v[32:35], v[176:179], v[208:211], v[32:35]
	v_mfma_f32_16x16x32_bf16 v[68:71], v[172:175], v[188:191], v[68:71]
	v_mfma_f32_16x16x32_bf16 v[64:67], v[180:183], v[188:191], v[64:67]
	v_mfma_f32_16x16x32_bf16 v[52:55], v[172:175], v[196:199], v[52:55]
	v_mfma_f32_16x16x32_bf16 v[48:51], v[180:183], v[196:199], v[48:51]
	v_mfma_f32_16x16x32_bf16 v[44:47], v[172:175], v[204:207], v[44:47]
	v_mfma_f32_16x16x32_bf16 v[40:43], v[180:183], v[204:207], v[40:43]
	v_mfma_f32_16x16x32_bf16 v[36:39], v[172:175], v[212:215], v[36:39]
	v_mfma_f32_16x16x32_bf16 v[32:35], v[180:183], v[212:215], v[32:35]
	s_setprio 0
	s_barrier
	s_add_i32 s20, s24, s94
	s_add_u32 s98, s28, 0x80
	s_addc_u32 s99, s29, 0
	s_mov_b32 m0, s20
	s_nop 0
	global_load_lds_dwordx4 v132, s[98:99]
	s_add_i32 m0, s20, 0x2000
	s_add_u32 s20, s28, 0x160080
	s_addc_u32 s21, s29, 0
	s_add_i32 s24, s25, s94
	global_load_lds_dwordx4 v128, s[98:99]
	s_mov_b32 m0, s24
	s_nop 0
	global_load_lds_dwordx4 v132, s[20:21]
	s_add_i32 m0, s24, 0x2000
	s_nop 0
	global_load_lds_dwordx4 v128, s[20:21]
	s_add_u32 s100, s30, 0x80
	s_addc_u32 s101, s31, 0
	s_mov_b32 m0, s36
	s_nop 0
	global_load_lds_dwordx4 v134, s[100:101]
	s_mov_b32 m0, s37
	s_nop 0
	global_load_lds_dwordx4 v130, s[100:101]
	ds_read_b128 v[184:187], v155 offset:49152
	ds_read_b128 v[188:191], v155 offset:50176
	ds_read_b128 v[192:195], v155 offset:51200
	ds_read_b128 v[196:199], v155 offset:52224
	ds_read_b128 v[200:203], v155 offset:53248
	ds_read_b128 v[204:207], v155 offset:54272
	ds_read_b128 v[208:211], v155 offset:55296
	ds_read_b128 v[212:215], v155 offset:56320
	s_waitcnt vmcnt(8)
	s_waitcnt lgkmcnt(0)
	s_barrier
	s_setprio 1
	v_mfma_f32_16x16x32_bf16 v[92:95], v[144:147], v[184:187], v[92:95]
	v_mfma_f32_16x16x32_bf16 v[88:91], v[160:163], v[184:187], v[88:91]
	v_mfma_f32_16x16x32_bf16 v[84:87], v[144:147], v[192:195], v[84:87]
	v_mfma_f32_16x16x32_bf16 v[80:83], v[160:163], v[192:195], v[80:83]
	v_mfma_f32_16x16x32_bf16 v[76:79], v[144:147], v[200:203], v[76:79]
	v_mfma_f32_16x16x32_bf16 v[72:75], v[160:163], v[200:203], v[72:75]
	v_mfma_f32_16x16x32_bf16 v[60:63], v[144:147], v[208:211], v[60:63]
	v_mfma_f32_16x16x32_bf16 v[56:59], v[160:163], v[208:211], v[56:59]
	v_mfma_f32_16x16x32_bf16 v[92:95], v[156:159], v[188:191], v[92:95]
	v_mfma_f32_16x16x32_bf16 v[88:91], v[164:167], v[188:191], v[88:91]
	v_mfma_f32_16x16x32_bf16 v[84:87], v[156:159], v[196:199], v[84:87]
	v_mfma_f32_16x16x32_bf16 v[80:83], v[164:167], v[196:199], v[80:83]
	v_mfma_f32_16x16x32_bf16 v[76:79], v[156:159], v[204:207], v[76:79]
	v_mfma_f32_16x16x32_bf16 v[72:75], v[164:167], v[204:207], v[72:75]
	v_mfma_f32_16x16x32_bf16 v[60:63], v[156:159], v[212:215], v[60:63]
	v_mfma_f32_16x16x32_bf16 v[56:59], v[164:167], v[212:215], v[56:59]
	v_mfma_f32_16x16x32_bf16 v[28:31], v[168:171], v[184:187], v[28:31]
	v_mfma_f32_16x16x32_bf16 v[24:27], v[176:179], v[184:187], v[24:27]
	v_mfma_f32_16x16x32_bf16 v[20:23], v[168:171], v[192:195], v[20:23]
	v_mfma_f32_16x16x32_bf16 v[16:19], v[176:179], v[192:195], v[16:19]
	v_mfma_f32_16x16x32_bf16 v[12:15], v[168:171], v[200:203], v[12:15]
	v_mfma_f32_16x16x32_bf16 v[8:11], v[176:179], v[200:203], v[8:11]
	v_mfma_f32_16x16x32_bf16 v[4:7], v[168:171], v[208:211], v[4:7]
	v_mfma_f32_16x16x32_bf16 v[0:3], v[176:179], v[208:211], v[0:3]
	v_mfma_f32_16x16x32_bf16 v[28:31], v[172:175], v[188:191], v[28:31]
	v_mfma_f32_16x16x32_bf16 v[24:27], v[180:183], v[188:191], v[24:27]
	v_mfma_f32_16x16x32_bf16 v[20:23], v[172:175], v[196:199], v[20:23]
	v_mfma_f32_16x16x32_bf16 v[16:19], v[180:183], v[196:199], v[16:19]
	v_mfma_f32_16x16x32_bf16 v[12:15], v[172:175], v[204:207], v[12:15]
	v_mfma_f32_16x16x32_bf16 v[8:11], v[180:183], v[204:207], v[8:11]
	v_mfma_f32_16x16x32_bf16 v[4:7], v[172:175], v[212:215], v[4:7]
	v_mfma_f32_16x16x32_bf16 v[0:3], v[180:183], v[212:215], v[0:3]
	s_setprio 0
	s_barrier
	s_add_i32 s45, s45, 2
	s_add_u32 s43, s43, 0x100
	s_addc_u32 s44, s44, 0
	s_cmpk_gt_u32 s45, 0x55
	s_mov_b64 s[20:21], s[26:27]
	s_cbranch_scc0 .LBB0_1810
	s_and_b64 vcc, exec, s[22:23]
	s_cbranch_vccz .LBB0_1813
	s_barrier
